# GEMM transition (epilogue, next-unit setup, first load segment) runs at s_setprio 2 against the partner half's prio-1 MFMA segment
# speedup vs baseline: 1.0065x; 1.0009x over previous
; #define PG8_STAGE(bufoff, gbase, voff) do { _Pragma("unroll") for (int _i = 0; _i < 2; ++_i) \
;         __builtin_amdgcn_global_load_lds((const unsigned*)((const char*)(gbase) + (voff)[_i]), (LAS unsigned*)(lds + (bufoff) + ldsw + _i * 8192), 16, 0, 0); } while (0)
; #define PG8_LDA(dst, b, h) do { _Pragma("unroll") for (int m = 0; m < 4; ++m) _Pragma("unroll") for (int k = 0; k < 2; ++k) dst[m][k] = *(const LAS bf16x8*)(lds + PG8_SA(b, h) + aoff + m * 2048 + k * 1024); } while (0)
; #define PG8_LDB(dst, b, h) do { _Pragma("unroll") for (int n = 0; n < 2; ++n) _Pragma("unroll") for (int k = 0; k < 2; ++k) dst[n][k] = *(const LAS bf16x8*)(lds + PG8_SB(b, h) + boff + n * 2048 + k * 1024); } while (0)
; #define PG8_MMA(ai, bj, At, Bt) do { __builtin_amdgcn_s_setprio(1); _Pragma("unroll") for (int m = 0; m < 4; ++m) _Pragma("unroll") for (int n = 0; n < 2; ++n) _Pragma("unroll") for (int k = 0; k < 2; ++k) \
;         acc[ai][bj][m][n] = __builtin_amdgcn_mfma_f32_16x16x32_bf16(Bt[n][k], At[m][k], acc[ai][bj][m][n], 0, 0, 0); __builtin_amdgcn_s_setprio(0); } while (0)
; #define PG8_WAIT_V(n) asm volatile("s_waitcnt vmcnt(" #n ")" ::: "memory")
; #define PG8_WAIT_L(n) asm volatile("s_waitcnt lgkmcnt(" #n ")" ::: "memory")
; #define PG8_BAR __builtin_amdgcn_s_barrier()
; #define PG8_SCHED __builtin_amdgcn_sched_barrier(0)
; template <class Epi, class Sched, bool ALIGN_EPI>
; __device__ __forceinline__ void gemm_phase(LAS unsigned char* lds, const int wid, const int lda_, const int ldb_, const int K_, const Sched& S, const Epi& E) {
;     ...
;             PG8_LDB(B0, 1, 0); PG8_LDB(B1, 1, 1); PG8_SCHED; PG8_LDA(At, 1, 0); PG8_STAGE(PG8_SA(0, 1), a2 + hstepA, voffA);
;             PG8_WAIT_V(8); PG8_WAIT_L(0); PG8_BAR; PG8_MMA(0, 0, At, B0); PG8_MMA(0, 1, At, B1); PG8_BAR; PG8_SCHED;
.Lgemm_join_299:
	s_add_i32 s17, 0, 0x18000
	v_add_u32_e32 v141, s17, v135
	s_add_i32 s27, 0, 0x1c000
	ds_read_b128 v[160:163], v141
	ds_read_b128 v[164:167], v141 offset:1024
	ds_read_b128 v[168:171], v141 offset:2048
	ds_read_b128 v[172:175], v141 offset:3072
	v_add_u32_e32 v141, s27, v135
	ds_read_b128 v[180:183], v141
	ds_read_b128 v[184:187], v141 offset:1024
	ds_read_b128 v[188:191], v141 offset:2048
	ds_read_b128 v[192:195], v141 offset:3072
	s_add_u32 s50, s50, s0
	s_addc_u32 s51, s51, s1
	s_mov_b32 m0, s26
	v_lshl_add_u64 v[248:249], s[50:51], 0, v[132:133]
	ds_read_b128 v[196:199], v139 offset:32768
	ds_read_b128 v[200:203], v139 offset:33792
	ds_read_b128 v[204:207], v139 offset:34816
	ds_read_b128 v[208:211], v139 offset:35840
	ds_read_b128 v[212:215], v139 offset:36864
	ds_read_b128 v[216:219], v139 offset:37888
	ds_read_b128 v[220:223], v139 offset:38912
	ds_read_b128 v[224:227], v139 offset:39936
	global_load_lds_dwordx4 v[248:249], off
	v_lshl_add_u64 v[248:249], s[50:51], 0, v[130:131]
	s_mov_b32 m0, s72
	s_nop 0
	global_load_lds_dwordx4 v[248:249], off
	s_waitcnt vmcnt(8)
	s_waitcnt lgkmcnt(0)
	s_barrier
	s_setprio 1
	s_waitcnt lgkmcnt(0)
	v_mfma_f32_16x16x32_bf16 v[124:127], v[160:163], v[196:199], v[124:127]
	v_mfma_f32_16x16x32_bf16 v[120:123], v[168:171], v[196:199], v[120:123]
	v_mfma_f32_16x16x32_bf16 v[116:119], v[160:163], v[204:207], v[116:119]
	v_mfma_f32_16x16x32_bf16 v[112:115], v[168:171], v[204:207], v[112:115]
	v_mfma_f32_16x16x32_bf16 v[100:103], v[160:163], v[212:215], v[100:103]
	v_mfma_f32_16x16x32_bf16 v[96:99], v[168:171], v[212:215], v[96:99]
	v_mfma_f32_16x16x32_bf16 v[84:87], v[160:163], v[220:223], v[84:87]
	v_mfma_f32_16x16x32_bf16 v[80:83], v[168:171], v[220:223], v[80:83]
	v_mfma_f32_16x16x32_bf16 v[124:127], v[164:167], v[200:203], v[124:127]
	v_mfma_f32_16x16x32_bf16 v[120:123], v[172:175], v[200:203], v[120:123]
	v_mfma_f32_16x16x32_bf16 v[116:119], v[164:167], v[208:211], v[116:119]
	v_mfma_f32_16x16x32_bf16 v[112:115], v[172:175], v[208:211], v[112:115]
	v_mfma_f32_16x16x32_bf16 v[100:103], v[164:167], v[216:219], v[100:103]
	v_mfma_f32_16x16x32_bf16 v[96:99], v[172:175], v[216:219], v[96:99]
	v_mfma_f32_16x16x32_bf16 v[84:87], v[164:167], v[224:227], v[84:87]
	v_mfma_f32_16x16x32_bf16 v[80:83], v[172:175], v[224:227], v[80:83]
	s_setprio 0
	s_setprio 1
	v_mfma_f32_16x16x32_bf16 v[108:111], v[180:183], v[196:199], v[108:111]
	v_mfma_f32_16x16x32_bf16 v[104:107], v[188:191], v[196:199], v[104:107]
	v_mfma_f32_16x16x32_bf16 v[92:95], v[180:183], v[204:207], v[92:95]
	v_mfma_f32_16x16x32_bf16 v[88:91], v[188:191], v[204:207], v[88:91]
	v_mfma_f32_16x16x32_bf16 v[76:79], v[180:183], v[212:215], v[76:79]
	v_mfma_f32_16x16x32_bf16 v[72:75], v[188:191], v[212:215], v[72:75]
	v_mfma_f32_16x16x32_bf16 v[68:71], v[180:183], v[220:223], v[68:71]
	v_mfma_f32_16x16x32_bf16 v[64:67], v[188:191], v[220:223], v[64:67]
	v_mfma_f32_16x16x32_bf16 v[108:111], v[184:187], v[200:203], v[108:111]
	v_mfma_f32_16x16x32_bf16 v[104:107], v[192:195], v[200:203], v[104:107]
	v_mfma_f32_16x16x32_bf16 v[92:95], v[184:187], v[208:211], v[92:95]
	v_mfma_f32_16x16x32_bf16 v[88:91], v[192:195], v[208:211], v[88:91]
	v_mfma_f32_16x16x32_bf16 v[76:79], v[184:187], v[216:219], v[76:79]
	v_mfma_f32_16x16x32_bf16 v[72:75], v[192:195], v[216:219], v[72:75]
	v_mfma_f32_16x16x32_bf16 v[68:71], v[184:187], v[224:227], v[68:71]
	v_mfma_f32_16x16x32_bf16 v[64:67], v[192:195], v[224:227], v[64:67]
	s_setprio 0
	s_barrier
; #define PG8_STAGE(bufoff, gbase, voff) do { _Pragma("unroll") for (int _i = 0; _i < 2; ++_i) \
;         __builtin_amdgcn_global_load_lds((const unsigned*)((const char*)(gbase) + (voff)[_i]), (LAS unsigned*)(lds + (bufoff) + ldsw + _i * 8192), 16, 0, 0); } while (0)
; #define PG8_LDA(dst, b, h) do { _Pragma("unroll") for (int m = 0; m < 4; ++m) _Pragma("unroll") for (int k = 0; k < 2; ++k) dst[m][k] = *(const LAS bf16x8*)(lds + PG8_SA(b, h) + aoff + m * 2048 + k * 1024); } while (0)
; #define PG8_MMA(ai, bj, At, Bt) do { __builtin_amdgcn_s_setprio(1); _Pragma("unroll") for (int m = 0; m < 4; ++m) _Pragma("unroll") for (int n = 0; n < 2; ++n) _Pragma("unroll") for (int k = 0; k < 2; ++k) \
;         acc[ai][bj][m][n] = __builtin_amdgcn_mfma_f32_16x16x32_bf16(Bt[n][k], At[m][k], acc[ai][bj][m][n], 0, 0, 0); __builtin_amdgcn_s_setprio(0); } while (0)
; #define PG8_WAIT_V(n) asm volatile("s_waitcnt vmcnt(" #n ")" ::: "memory")
; #define PG8_WAIT_L(n) asm volatile("s_waitcnt lgkmcnt(" #n ")" ::: "memory")
; #define PG8_BAR __builtin_amdgcn_s_barrier()
; #define PG8_SCHED __builtin_amdgcn_sched_barrier(0)
; template <class Epi, class Sched, bool ALIGN_EPI>
; __device__ __forceinline__ void gemm_phase(LAS unsigned char* lds, const int wid, const int lda_, const int ldb_, const int K_, const Sched& S, const Epi& E) {
;     ...
;             PG8_LDA(At, 1, 1); PG8_STAGE(PG8_SB(1, 0), b3, voffB); PG8_STAGE(PG8_SB(1, 1), b3 + hstepB, voffB); PG8_STAGE(PG8_SA(1, 0), a3, voffA);
;             PG8_WAIT_V(8); PG8_WAIT_L(0); PG8_BAR; PG8_MMA(1, 0, At, B0); PG8_MMA(1, 1, At, B1); PG8_BAR; PG8_SCHED;
;         }
;         if constexpr (ALIGN_EPI) { if (wr == 0) PG8_BAR; }
;         E(acc, cur, S, wr, wc, fr, fq);
;     __device__ __forceinline__ void out(const pg8::Unit& u, char*& o, int& ldo, int& kind) const {
;         if (u.pn < 24) { o = (char*)ws + WS_XBCP + ((size_t)u.pm * 256 * XBC + (size_t)u.pn * 256) * 2; ldo = XBC; kind = 0; }
;         else if (u.pn < 40) { o = (char*)ws + WS_Z + ((size_t)u.pm * 256 * DI + (size_t)(u.pn - 24) * 256) * 2; ldo = DI; kind = 0; }
;         else { o = (char*)ws + WS_DT + (size_t)u.pm * 256 * 128 * 4; ldo = 128; kind = 1; } }
	s_add_i32 s17, s17, s3
	v_lshl_add_u64 v[228:229], v[228:229], 0, s[24:25]
	s_mov_b32 m0, s17
	ds_read_b128 v[196:199], v139 offset:49152
	ds_read_b128 v[200:203], v139 offset:50176
	ds_read_b128 v[204:207], v139 offset:51200
	ds_read_b128 v[208:211], v139 offset:52224
	ds_read_b128 v[212:215], v139 offset:53248
	ds_read_b128 v[216:219], v139 offset:54272
	ds_read_b128 v[220:223], v139 offset:55296
	ds_read_b128 v[224:227], v139 offset:56320
	global_load_lds_dwordx4 v[228:229], off
	v_lshl_add_u64 v[228:229], v[230:231], 0, s[24:25]
	s_add_i32 m0, s17, 0x2000
	s_add_i32 s17, s27, s3
	global_load_lds_dwordx4 v[228:229], off
	v_lshl_add_u64 v[228:229], v[232:233], 0, s[24:25]
	s_mov_b32 m0, s17
	s_nop 0
	global_load_lds_dwordx4 v[228:229], off
	v_lshl_add_u64 v[228:229], v[234:235], 0, s[24:25]
	s_add_i32 m0, s17, 0x2000
	s_nop 0
	global_load_lds_dwordx4 v[228:229], off
	v_lshl_add_u64 v[228:229], v[236:237], 0, s[24:25]
	s_mov_b32 m0, s73
	s_nop 0
	global_load_lds_dwordx4 v[228:229], off
	v_lshl_add_u64 v[228:229], v[246:247], 0, s[24:25]
	s_mov_b32 m0, s74
	s_nop 0
	global_load_lds_dwordx4 v[228:229], off
	s_waitcnt vmcnt(8)
	s_waitcnt lgkmcnt(0)
	s_barrier
	s_setprio 1
	s_waitcnt lgkmcnt(0)
	v_mfma_f32_16x16x32_bf16 v[60:63], v[160:163], v[196:199], v[60:63]
	v_mfma_f32_16x16x32_bf16 v[56:59], v[168:171], v[196:199], v[56:59]
	v_mfma_f32_16x16x32_bf16 v[52:55], v[160:163], v[204:207], v[52:55]
	v_mfma_f32_16x16x32_bf16 v[48:51], v[168:171], v[204:207], v[48:51]
	v_mfma_f32_16x16x32_bf16 v[36:39], v[160:163], v[212:215], v[36:39]
	v_mfma_f32_16x16x32_bf16 v[32:35], v[168:171], v[212:215], v[32:35]
	v_mfma_f32_16x16x32_bf16 v[20:23], v[160:163], v[220:223], v[20:23]
	v_mfma_f32_16x16x32_bf16 v[16:19], v[168:171], v[220:223], v[16:19]
	v_mfma_f32_16x16x32_bf16 v[60:63], v[164:167], v[200:203], v[60:63]
	v_mfma_f32_16x16x32_bf16 v[56:59], v[172:175], v[200:203], v[56:59]
	v_mfma_f32_16x16x32_bf16 v[52:55], v[164:167], v[208:211], v[52:55]
	v_mfma_f32_16x16x32_bf16 v[48:51], v[172:175], v[208:211], v[48:51]
	v_mfma_f32_16x16x32_bf16 v[36:39], v[164:167], v[216:219], v[36:39]
	v_mfma_f32_16x16x32_bf16 v[32:35], v[172:175], v[216:219], v[32:35]
	v_mfma_f32_16x16x32_bf16 v[20:23], v[164:167], v[224:227], v[20:23]
	v_mfma_f32_16x16x32_bf16 v[16:19], v[172:175], v[224:227], v[16:19]
	s_setprio 0
	s_setprio 1
	v_mfma_f32_16x16x32_bf16 v[44:47], v[180:183], v[196:199], v[44:47]
	v_mfma_f32_16x16x32_bf16 v[40:43], v[188:191], v[196:199], v[40:43]
	v_mfma_f32_16x16x32_bf16 v[28:31], v[180:183], v[204:207], v[28:31]
	v_mfma_f32_16x16x32_bf16 v[24:27], v[188:191], v[204:207], v[24:27]
	v_mfma_f32_16x16x32_bf16 v[12:15], v[180:183], v[212:215], v[12:15]
	v_mfma_f32_16x16x32_bf16 v[8:11], v[188:191], v[212:215], v[8:11]
	v_mfma_f32_16x16x32_bf16 v[4:7], v[180:183], v[220:223], v[4:7]
	v_mfma_f32_16x16x32_bf16 v[0:3], v[188:191], v[220:223], v[0:3]
	v_mfma_f32_16x16x32_bf16 v[44:47], v[184:187], v[200:203], v[44:47]
	v_mfma_f32_16x16x32_bf16 v[40:43], v[192:195], v[200:203], v[40:43]
	v_mfma_f32_16x16x32_bf16 v[28:31], v[184:187], v[208:211], v[28:31]
	v_mfma_f32_16x16x32_bf16 v[24:27], v[192:195], v[208:211], v[24:27]
	v_mfma_f32_16x16x32_bf16 v[12:15], v[184:187], v[216:219], v[12:15]
	v_mfma_f32_16x16x32_bf16 v[8:11], v[192:195], v[216:219], v[8:11]
	v_mfma_f32_16x16x32_bf16 v[4:7], v[184:187], v[224:227], v[4:7]
	v_mfma_f32_16x16x32_bf16 v[0:3], v[192:195], v[224:227], v[0:3]
	s_setprio 0
	s_barrier
	s_add_i32 s76, s76, 2
	s_add_u32 s48, s48, 0x100
	s_addc_u32 s49, s49, 0
	s_cmp_gt_u32 s76, 29
	s_cbranch_scc0 .LBB0_299
	s_setprio 2
	s_ashr_i32 s45, s44, 31
	s_cmp_gt_i32 s30, 23
	s_mov_b64 s[48:49], -1
	s_cbranch_scc0 .LBB0_305
	s_cmp_gt_u32 s30, 39
	s_mov_b64 s[4:5], -1
	s_cbranch_scc0 .LBB0_303
	s_lshl_b64 s[4:5], s[44:45], 17
	v_readlane_b32 s46, v252, 60
	v_readlane_b32 s47, v252, 61
	s_add_u32 s46, s46, s4
	s_addc_u32 s47, s47, s5
	s_mov_b64 s[4:5], 0

; #define PG8_STAGE(bufoff, gbase, voff) do { _Pragma("unroll") for (int _i = 0; _i < 2; ++_i) \
;         __builtin_amdgcn_global_load_lds((const unsigned*)((const char*)(gbase) + (voff)[_i]), (LAS unsigned*)(lds + (bufoff) + ldsw + _i * 8192), 16, 0, 0); } while (0)
; #define PG8_LDA(dst, b, h) do { _Pragma("unroll") for (int m = 0; m < 4; ++m) _Pragma("unroll") for (int k = 0; k < 2; ++k) dst[m][k] = *(const LAS bf16x8*)(lds + PG8_SA(b, h) + aoff + m * 2048 + k * 1024); } while (0)
; #define PG8_LDB(dst, b, h) do { _Pragma("unroll") for (int n = 0; n < 2; ++n) _Pragma("unroll") for (int k = 0; k < 2; ++k) dst[n][k] = *(const LAS bf16x8*)(lds + PG8_SB(b, h) + boff + n * 2048 + k * 1024); } while (0)
; #define PG8_MMA(ai, bj, At, Bt) do { __builtin_amdgcn_s_setprio(1); _Pragma("unroll") for (int m = 0; m < 4; ++m) _Pragma("unroll") for (int n = 0; n < 2; ++n) _Pragma("unroll") for (int k = 0; k < 2; ++k) \
;         acc[ai][bj][m][n] = __builtin_amdgcn_mfma_f32_16x16x32_bf16(Bt[n][k], At[m][k], acc[ai][bj][m][n], 0, 0, 0); __builtin_amdgcn_s_setprio(0); } while (0)
; #define PG8_WAIT_V(n) asm volatile("s_waitcnt vmcnt(" #n ")" ::: "memory")
; #define PG8_WAIT_L(n) asm volatile("s_waitcnt lgkmcnt(" #n ")" ::: "memory")
; #define PG8_BAR __builtin_amdgcn_s_barrier()
; #define PG8_SCHED __builtin_amdgcn_sched_barrier(0)
; template <class Epi, class Sched, bool ALIGN_EPI>
; __device__ __forceinline__ void gemm_phase(LAS unsigned char* lds, const int wid, const int lda_, const int ldb_, const int K_, const Sched& S, const Epi& E) {
;     ...
;             PG8_LDB(B0, 1, 0); PG8_LDB(B1, 1, 1); PG8_SCHED; PG8_LDA(At, 1, 0); PG8_STAGE(PG8_SA(0, 1), a2 + hstepA, voffA);
;             PG8_WAIT_V(8); PG8_WAIT_L(0); PG8_BAR; PG8_MMA(0, 0, At, B0); PG8_MMA(0, 1, At, B1); PG8_BAR; PG8_SCHED;
.Lgemm_join_671:
	s_add_i32 s17, 0, 0x18000
	v_add_u32_e32 v141, s17, v135
	s_add_i32 s27, 0, 0x1c000
	ds_read_b128 v[156:159], v141
	ds_read_b128 v[160:163], v141 offset:1024
	ds_read_b128 v[164:167], v141 offset:2048
	ds_read_b128 v[168:171], v141 offset:3072
	v_add_u32_e32 v141, s27, v135
	ds_read_b128 v[172:175], v141
	ds_read_b128 v[180:183], v141 offset:1024
	ds_read_b128 v[184:187], v141 offset:2048
	ds_read_b128 v[188:191], v141 offset:3072
	s_add_u32 s80, s96, s10
	s_addc_u32 s81, s97, s11
	s_mov_b32 m0, s15
	v_lshl_add_u64 v[236:237], s[80:81], 0, v[128:129]
	ds_read_b128 v[192:195], v139 offset:32768
	ds_read_b128 v[196:199], v139 offset:33792
	ds_read_b128 v[200:203], v139 offset:34816
	ds_read_b128 v[204:207], v139 offset:35840
	ds_read_b128 v[208:211], v139 offset:36864
	ds_read_b128 v[212:215], v139 offset:37888
	ds_read_b128 v[216:219], v139 offset:38912
	ds_read_b128 v[220:223], v139 offset:39936
	global_load_lds_dwordx4 v[236:237], off
	v_lshl_add_u64 v[236:237], s[80:81], 0, v[130:131]
	s_mov_b32 m0, s26
	s_nop 0
	global_load_lds_dwordx4 v[236:237], off
	s_waitcnt vmcnt(8)
	s_waitcnt lgkmcnt(0)
	s_barrier
	s_setprio 1
	s_waitcnt lgkmcnt(0)
	v_mfma_f32_16x16x32_bf16 v[124:127], v[156:159], v[192:195], v[124:127]
	v_mfma_f32_16x16x32_bf16 v[120:123], v[164:167], v[192:195], v[120:123]
	v_mfma_f32_16x16x32_bf16 v[116:119], v[156:159], v[200:203], v[116:119]
	v_mfma_f32_16x16x32_bf16 v[112:115], v[164:167], v[200:203], v[112:115]
	v_mfma_f32_16x16x32_bf16 v[100:103], v[156:159], v[208:211], v[100:103]
	v_mfma_f32_16x16x32_bf16 v[96:99], v[164:167], v[208:211], v[96:99]
	v_mfma_f32_16x16x32_bf16 v[84:87], v[156:159], v[216:219], v[84:87]
	v_mfma_f32_16x16x32_bf16 v[80:83], v[164:167], v[216:219], v[80:83]
	v_mfma_f32_16x16x32_bf16 v[124:127], v[160:163], v[196:199], v[124:127]
	v_mfma_f32_16x16x32_bf16 v[120:123], v[168:171], v[196:199], v[120:123]
	v_mfma_f32_16x16x32_bf16 v[116:119], v[160:163], v[204:207], v[116:119]
	v_mfma_f32_16x16x32_bf16 v[112:115], v[168:171], v[204:207], v[112:115]
	v_mfma_f32_16x16x32_bf16 v[100:103], v[160:163], v[212:215], v[100:103]
	v_mfma_f32_16x16x32_bf16 v[96:99], v[168:171], v[212:215], v[96:99]
	v_mfma_f32_16x16x32_bf16 v[84:87], v[160:163], v[220:223], v[84:87]
	v_mfma_f32_16x16x32_bf16 v[80:83], v[168:171], v[220:223], v[80:83]
	s_setprio 0
	s_setprio 1
	v_mfma_f32_16x16x32_bf16 v[108:111], v[172:175], v[192:195], v[108:111]
	v_mfma_f32_16x16x32_bf16 v[104:107], v[184:187], v[192:195], v[104:107]
	v_mfma_f32_16x16x32_bf16 v[92:95], v[172:175], v[200:203], v[92:95]
	v_mfma_f32_16x16x32_bf16 v[88:91], v[184:187], v[200:203], v[88:91]
	v_mfma_f32_16x16x32_bf16 v[76:79], v[172:175], v[208:211], v[76:79]
	v_mfma_f32_16x16x32_bf16 v[72:75], v[184:187], v[208:211], v[72:75]
	v_mfma_f32_16x16x32_bf16 v[68:71], v[172:175], v[216:219], v[68:71]
	v_mfma_f32_16x16x32_bf16 v[64:67], v[184:187], v[216:219], v[64:67]
	v_mfma_f32_16x16x32_bf16 v[108:111], v[180:183], v[196:199], v[108:111]
	v_mfma_f32_16x16x32_bf16 v[104:107], v[188:191], v[196:199], v[104:107]
	v_mfma_f32_16x16x32_bf16 v[92:95], v[180:183], v[204:207], v[92:95]
	v_mfma_f32_16x16x32_bf16 v[88:91], v[188:191], v[204:207], v[88:91]
	v_mfma_f32_16x16x32_bf16 v[76:79], v[180:183], v[212:215], v[76:79]
	v_mfma_f32_16x16x32_bf16 v[72:75], v[188:191], v[212:215], v[72:75]
	v_mfma_f32_16x16x32_bf16 v[68:71], v[180:183], v[220:223], v[68:71]
	v_mfma_f32_16x16x32_bf16 v[64:67], v[188:191], v[220:223], v[64:67]
	s_setprio 0
	s_barrier
; #define PG8_STAGE(bufoff, gbase, voff) do { _Pragma("unroll") for (int _i = 0; _i < 2; ++_i) \
;         __builtin_amdgcn_global_load_lds((const unsigned*)((const char*)(gbase) + (voff)[_i]), (LAS unsigned*)(lds + (bufoff) + ldsw + _i * 8192), 16, 0, 0); } while (0)
; #define PG8_LDA(dst, b, h) do { _Pragma("unroll") for (int m = 0; m < 4; ++m) _Pragma("unroll") for (int k = 0; k < 2; ++k) dst[m][k] = *(const LAS bf16x8*)(lds + PG8_SA(b, h) + aoff + m * 2048 + k * 1024); } while (0)
; #define PG8_MMA(ai, bj, At, Bt) do { __builtin_amdgcn_s_setprio(1); _Pragma("unroll") for (int m = 0; m < 4; ++m) _Pragma("unroll") for (int n = 0; n < 2; ++n) _Pragma("unroll") for (int k = 0; k < 2; ++k) \
;         acc[ai][bj][m][n] = __builtin_amdgcn_mfma_f32_16x16x32_bf16(Bt[n][k], At[m][k], acc[ai][bj][m][n], 0, 0, 0); __builtin_amdgcn_s_setprio(0); } while (0)
; #define PG8_WAIT_V(n) asm volatile("s_waitcnt vmcnt(" #n ")" ::: "memory")
; #define PG8_WAIT_L(n) asm volatile("s_waitcnt lgkmcnt(" #n ")" ::: "memory")
; #define PG8_BAR __builtin_amdgcn_s_barrier()
; #define PG8_SCHED __builtin_amdgcn_sched_barrier(0)
; template <class Epi, class Sched, bool ALIGN_EPI>
; __device__ __forceinline__ void gemm_phase(LAS unsigned char* lds, const int wid, const int lda_, const int ldb_, const int K_, const Sched& S, const Epi& E) {
;     ...
;             PG8_LDA(At, 1, 1); PG8_STAGE(PG8_SB(1, 0), b3, voffB); PG8_STAGE(PG8_SB(1, 1), b3 + hstepB, voffB); PG8_STAGE(PG8_SA(1, 0), a3, voffA);
;             PG8_WAIT_V(8); PG8_WAIT_L(0); PG8_BAR; PG8_MMA(1, 0, At, B0); PG8_MMA(1, 1, At, B1); PG8_BAR; PG8_SCHED;
;         }
;         if constexpr (ALIGN_EPI) { if (wr == 0) PG8_BAR; }
;         E(acc, cur, S, wr, wc, fr, fq);
;         if (!has_next) break;
;     __device__ __forceinline__ void out(const pg8::Unit& u, char*& o, int& ldo, int& kind) const { ldo = D;
;         if (u.kq < 0) { o = (char*)ws + YOFF + ((size_t)u.pm * 256 * D + (size_t)u.pn * 256) * 2; kind = 0; }
;         else { o = (char*)ws + WS_PART + (((size_t)u.kq * MCTX + (size_t)(u.pm - 64) * 256) * D + (size_t)u.pn * 256) * 2; kind = 0; } }
	s_add_i32 s17, s17, s3
	v_lshl_add_u64 v[224:225], v[224:225], 0, s[24:25]
	s_mov_b32 m0, s17
	ds_read_b128 v[192:195], v139 offset:49152
	ds_read_b128 v[196:199], v139 offset:50176
	ds_read_b128 v[200:203], v139 offset:51200
	ds_read_b128 v[204:207], v139 offset:52224
	ds_read_b128 v[208:211], v139 offset:53248
	ds_read_b128 v[212:215], v139 offset:54272
	ds_read_b128 v[216:219], v139 offset:55296
	ds_read_b128 v[220:223], v139 offset:56320
	global_load_lds_dwordx4 v[224:225], off
	v_lshl_add_u64 v[224:225], v[226:227], 0, s[24:25]
	s_add_i32 m0, s17, 0x2000
	s_add_i32 s17, s27, s3
	global_load_lds_dwordx4 v[224:225], off
	v_lshl_add_u64 v[224:225], v[228:229], 0, s[24:25]
	s_mov_b32 m0, s17
	s_nop 0
	global_load_lds_dwordx4 v[224:225], off
	v_lshl_add_u64 v[224:225], v[230:231], 0, s[24:25]
	s_add_i32 m0, s17, 0x2000
	s_nop 0
	global_load_lds_dwordx4 v[224:225], off
	v_lshl_add_u64 v[224:225], v[232:233], 0, s[24:25]
	s_mov_b32 m0, s72
	s_nop 0
	global_load_lds_dwordx4 v[224:225], off
	v_lshl_add_u64 v[224:225], v[234:235], 0, s[24:25]
	s_mov_b32 m0, s73
	s_nop 0
	global_load_lds_dwordx4 v[224:225], off
	s_waitcnt vmcnt(8)
	s_waitcnt lgkmcnt(0)
	s_barrier
	s_setprio 1
	s_waitcnt lgkmcnt(0)
	v_mfma_f32_16x16x32_bf16 v[60:63], v[156:159], v[192:195], v[60:63]
	v_mfma_f32_16x16x32_bf16 v[56:59], v[164:167], v[192:195], v[56:59]
	v_mfma_f32_16x16x32_bf16 v[52:55], v[156:159], v[200:203], v[52:55]
	v_mfma_f32_16x16x32_bf16 v[48:51], v[164:167], v[200:203], v[48:51]
	v_mfma_f32_16x16x32_bf16 v[36:39], v[156:159], v[208:211], v[36:39]
	v_mfma_f32_16x16x32_bf16 v[32:35], v[164:167], v[208:211], v[32:35]
	v_mfma_f32_16x16x32_bf16 v[20:23], v[156:159], v[216:219], v[20:23]
	v_mfma_f32_16x16x32_bf16 v[16:19], v[164:167], v[216:219], v[16:19]
	v_mfma_f32_16x16x32_bf16 v[60:63], v[160:163], v[196:199], v[60:63]
	v_mfma_f32_16x16x32_bf16 v[56:59], v[168:171], v[196:199], v[56:59]
	v_mfma_f32_16x16x32_bf16 v[52:55], v[160:163], v[204:207], v[52:55]
	v_mfma_f32_16x16x32_bf16 v[48:51], v[168:171], v[204:207], v[48:51]
	v_mfma_f32_16x16x32_bf16 v[36:39], v[160:163], v[212:215], v[36:39]
	v_mfma_f32_16x16x32_bf16 v[32:35], v[168:171], v[212:215], v[32:35]
	v_mfma_f32_16x16x32_bf16 v[20:23], v[160:163], v[220:223], v[20:23]
	v_mfma_f32_16x16x32_bf16 v[16:19], v[168:171], v[220:223], v[16:19]
	s_setprio 0
	s_setprio 1
	v_mfma_f32_16x16x32_bf16 v[44:47], v[172:175], v[192:195], v[44:47]
	v_mfma_f32_16x16x32_bf16 v[40:43], v[184:187], v[192:195], v[40:43]
	v_mfma_f32_16x16x32_bf16 v[28:31], v[172:175], v[200:203], v[28:31]
	v_mfma_f32_16x16x32_bf16 v[24:27], v[184:187], v[200:203], v[24:27]
	v_mfma_f32_16x16x32_bf16 v[12:15], v[172:175], v[208:211], v[12:15]
	v_mfma_f32_16x16x32_bf16 v[8:11], v[184:187], v[208:211], v[8:11]
	v_mfma_f32_16x16x32_bf16 v[4:7], v[172:175], v[216:219], v[4:7]
	v_mfma_f32_16x16x32_bf16 v[0:3], v[184:187], v[216:219], v[0:3]
	v_mfma_f32_16x16x32_bf16 v[44:47], v[180:183], v[196:199], v[44:47]
	v_mfma_f32_16x16x32_bf16 v[40:43], v[188:191], v[196:199], v[40:43]
	v_mfma_f32_16x16x32_bf16 v[28:31], v[180:183], v[204:207], v[28:31]
	v_mfma_f32_16x16x32_bf16 v[24:27], v[188:191], v[204:207], v[24:27]
	v_mfma_f32_16x16x32_bf16 v[12:15], v[180:183], v[212:215], v[12:15]
	v_mfma_f32_16x16x32_bf16 v[8:11], v[188:191], v[212:215], v[8:11]
	v_mfma_f32_16x16x32_bf16 v[4:7], v[180:183], v[220:223], v[4:7]
	v_mfma_f32_16x16x32_bf16 v[0:3], v[188:191], v[220:223], v[0:3]
	s_setprio 0
	s_barrier
	s_add_u32 s94, s94, 0x100
	s_addc_u32 s95, s95, 0
	s_add_u32 s43, s43, 0x100
	s_addc_u32 s76, s76, 0
	s_cmp_ge_u32 s78, s35
	s_mov_b32 s77, s78
	s_cbranch_scc0 .LBB0_671
	s_setprio 2
	s_mov_b64 s[94:95], -1
	s_and_b64 vcc, exec, s[50:51]
	s_cbranch_vccz .LBB0_674
	s_mov_b32 s39, s92
	s_ashr_i32 s35, s34, 31
	s_ashr_i32 s37, s36, 31
	s_lshl_b64 s[4:5], s[34:35], 20
	s_lshl_b64 s[50:51], s[36:37], 9
	s_lshl_b64 s[38:39], s[38:39], 23
	v_readlane_b32 s76, v251, 28
	v_readlane_b32 s77, v251, 29
	s_add_u32 s17, s76, s50
	s_addc_u32 s27, s77, s51
	s_add_u32 s17, s17, s38
	s_addc_u32 s27, s27, s39
	s_add_u32 s4, s17, s4
	s_addc_u32 s5, s27, s5
	s_add_u32 s4, s4, 0xfc000000
	s_addc_u32 s5, s5, -1
	s_mov_b64 s[94:95], 0

; #define PG8_STAGE(bufoff, gbase, voff) do { _Pragma("unroll") for (int _i = 0; _i < 2; ++_i) \
;         __builtin_amdgcn_global_load_lds((const unsigned*)((const char*)(gbase) + (voff)[_i]), (LAS unsigned*)(lds + (bufoff) + ldsw + _i * 8192), 16, 0, 0); } while (0)
; #define PG8_LDA(dst, b, h) do { _Pragma("unroll") for (int m = 0; m < 4; ++m) _Pragma("unroll") for (int k = 0; k < 2; ++k) dst[m][k] = *(const LAS bf16x8*)(lds + PG8_SA(b, h) + aoff + m * 2048 + k * 1024); } while (0)
; #define PG8_LDB(dst, b, h) do { _Pragma("unroll") for (int n = 0; n < 2; ++n) _Pragma("unroll") for (int k = 0; k < 2; ++k) dst[n][k] = *(const LAS bf16x8*)(lds + PG8_SB(b, h) + boff + n * 2048 + k * 1024); } while (0)
; #define PG8_MMA(ai, bj, At, Bt) do { __builtin_amdgcn_s_setprio(1); _Pragma("unroll") for (int m = 0; m < 4; ++m) _Pragma("unroll") for (int n = 0; n < 2; ++n) _Pragma("unroll") for (int k = 0; k < 2; ++k) \
;         acc[ai][bj][m][n] = __builtin_amdgcn_mfma_f32_16x16x32_bf16(Bt[n][k], At[m][k], acc[ai][bj][m][n], 0, 0, 0); __builtin_amdgcn_s_setprio(0); } while (0)
; #define PG8_WAIT_V(n) asm volatile("s_waitcnt vmcnt(" #n ")" ::: "memory")
; #define PG8_WAIT_L(n) asm volatile("s_waitcnt lgkmcnt(" #n ")" ::: "memory")
; #define PG8_BAR __builtin_amdgcn_s_barrier()
; #define PG8_SCHED __builtin_amdgcn_sched_barrier(0)
; template <class Epi, class Sched, bool ALIGN_EPI>
; __device__ __forceinline__ void gemm_phase(LAS unsigned char* lds, const int wid, const int lda_, const int ldb_, const int K_, const Sched& S, const Epi& E) {
;     ...
;             PG8_LDB(B0, 1, 0); PG8_LDB(B1, 1, 1); PG8_SCHED; PG8_LDA(At, 1, 0); PG8_STAGE(PG8_SA(0, 1), a2 + hstepA, voffA);
;             PG8_WAIT_V(8); PG8_WAIT_L(0); PG8_BAR; PG8_MMA(0, 0, At, B0); PG8_MMA(0, 1, At, B1); PG8_BAR; PG8_SCHED;
.Lgemm_join_697:
	v_add_u32_e32 v141, s79, v135
	ds_read_b128 v[152:155], v141
	ds_read_b128 v[156:159], v141 offset:1024
	ds_read_b128 v[160:163], v141 offset:2048
	ds_read_b128 v[164:167], v141 offset:3072
	v_add_u32_e32 v141, s78, v135
	ds_read_b128 v[168:171], v141
	ds_read_b128 v[172:175], v141 offset:1024
	ds_read_b128 v[180:183], v141 offset:2048
	ds_read_b128 v[184:187], v141 offset:3072
	s_mov_b32 m0, s7
	v_lshl_add_u64 v[232:233], s[48:49], 0, v[132:133]
	ds_read_b128 v[188:191], v139 offset:32768
	ds_read_b128 v[192:195], v139 offset:33792
	ds_read_b128 v[196:199], v139 offset:34816
	ds_read_b128 v[200:203], v139 offset:35840
	ds_read_b128 v[204:207], v139 offset:36864
	ds_read_b128 v[208:211], v139 offset:37888
	ds_read_b128 v[212:215], v139 offset:38912
	ds_read_b128 v[216:219], v139 offset:39936
	global_load_lds_dwordx4 v[232:233], off
	v_lshl_add_u64 v[232:233], s[48:49], 0, v[130:131]
	s_mov_b32 m0, s14
	s_nop 0
	global_load_lds_dwordx4 v[232:233], off
	s_waitcnt vmcnt(8)
	s_waitcnt lgkmcnt(0)
	s_barrier
	s_setprio 1
	s_waitcnt lgkmcnt(0)
	v_mfma_f32_16x16x32_bf16 v[124:127], v[152:155], v[188:191], v[124:127]
	v_mfma_f32_16x16x32_bf16 v[120:123], v[160:163], v[188:191], v[120:123]
	v_mfma_f32_16x16x32_bf16 v[116:119], v[152:155], v[196:199], v[116:119]
	v_mfma_f32_16x16x32_bf16 v[112:115], v[160:163], v[196:199], v[112:115]
	v_mfma_f32_16x16x32_bf16 v[100:103], v[152:155], v[204:207], v[100:103]
	v_mfma_f32_16x16x32_bf16 v[96:99], v[160:163], v[204:207], v[96:99]
	v_mfma_f32_16x16x32_bf16 v[84:87], v[152:155], v[212:215], v[84:87]
	v_mfma_f32_16x16x32_bf16 v[80:83], v[160:163], v[212:215], v[80:83]
	v_mfma_f32_16x16x32_bf16 v[124:127], v[156:159], v[192:195], v[124:127]
	v_mfma_f32_16x16x32_bf16 v[120:123], v[164:167], v[192:195], v[120:123]
	v_mfma_f32_16x16x32_bf16 v[116:119], v[156:159], v[200:203], v[116:119]
	v_mfma_f32_16x16x32_bf16 v[112:115], v[164:167], v[200:203], v[112:115]
	v_mfma_f32_16x16x32_bf16 v[100:103], v[156:159], v[208:211], v[100:103]
	v_mfma_f32_16x16x32_bf16 v[96:99], v[164:167], v[208:211], v[96:99]
	v_mfma_f32_16x16x32_bf16 v[84:87], v[156:159], v[216:219], v[84:87]
	v_mfma_f32_16x16x32_bf16 v[80:83], v[164:167], v[216:219], v[80:83]
	s_setprio 0
	s_setprio 1
	v_mfma_f32_16x16x32_bf16 v[108:111], v[168:171], v[188:191], v[108:111]
	v_mfma_f32_16x16x32_bf16 v[104:107], v[180:183], v[188:191], v[104:107]
	v_mfma_f32_16x16x32_bf16 v[92:95], v[168:171], v[196:199], v[92:95]
	v_mfma_f32_16x16x32_bf16 v[88:91], v[180:183], v[196:199], v[88:91]
	v_mfma_f32_16x16x32_bf16 v[76:79], v[168:171], v[204:207], v[76:79]
	v_mfma_f32_16x16x32_bf16 v[72:75], v[180:183], v[204:207], v[72:75]
	v_mfma_f32_16x16x32_bf16 v[68:71], v[168:171], v[212:215], v[68:71]
	v_mfma_f32_16x16x32_bf16 v[64:67], v[180:183], v[212:215], v[64:67]
	v_mfma_f32_16x16x32_bf16 v[108:111], v[172:175], v[192:195], v[108:111]
	v_mfma_f32_16x16x32_bf16 v[104:107], v[184:187], v[192:195], v[104:107]
	v_mfma_f32_16x16x32_bf16 v[92:95], v[172:175], v[200:203], v[92:95]
	v_mfma_f32_16x16x32_bf16 v[88:91], v[184:187], v[200:203], v[88:91]
	v_mfma_f32_16x16x32_bf16 v[76:79], v[172:175], v[208:211], v[76:79]
	v_mfma_f32_16x16x32_bf16 v[72:75], v[184:187], v[208:211], v[72:75]
	v_mfma_f32_16x16x32_bf16 v[68:71], v[172:175], v[216:219], v[68:71]
	v_mfma_f32_16x16x32_bf16 v[64:67], v[184:187], v[216:219], v[64:67]
	s_setprio 0
	s_barrier
; #define PG8_STAGE(bufoff, gbase, voff) do { _Pragma("unroll") for (int _i = 0; _i < 2; ++_i) \
;         __builtin_amdgcn_global_load_lds((const unsigned*)((const char*)(gbase) + (voff)[_i]), (LAS unsigned*)(lds + (bufoff) + ldsw + _i * 8192), 16, 0, 0); } while (0)
; #define PG8_LDA(dst, b, h) do { _Pragma("unroll") for (int m = 0; m < 4; ++m) _Pragma("unroll") for (int k = 0; k < 2; ++k) dst[m][k] = *(const LAS bf16x8*)(lds + PG8_SA(b, h) + aoff + m * 2048 + k * 1024); } while (0)
; #define PG8_MMA(ai, bj, At, Bt) do { __builtin_amdgcn_s_setprio(1); _Pragma("unroll") for (int m = 0; m < 4; ++m) _Pragma("unroll") for (int n = 0; n < 2; ++n) _Pragma("unroll") for (int k = 0; k < 2; ++k) \
;         acc[ai][bj][m][n] = __builtin_amdgcn_mfma_f32_16x16x32_bf16(Bt[n][k], At[m][k], acc[ai][bj][m][n], 0, 0, 0); __builtin_amdgcn_s_setprio(0); } while (0)
; #define PG8_WAIT_V(n) asm volatile("s_waitcnt vmcnt(" #n ")" ::: "memory")
; #define PG8_WAIT_L(n) asm volatile("s_waitcnt lgkmcnt(" #n ")" ::: "memory")
; #define PG8_BAR __builtin_amdgcn_s_barrier()
; #define PG8_SCHED __builtin_amdgcn_sched_barrier(0)
;     __device__ __forceinline__ const char* b(const pg8::Unit& u) const { return (const char*)ws + boff + (size_t)u.pn * 256 * K_ * 2 + (u.kq < 0 ? 0 : u.kq * (K_ / 4) * 2); }
; template <class Epi, class Sched, bool ALIGN_EPI>
; __device__ __forceinline__ void gemm_phase(LAS unsigned char* lds, const int wid, const int lda_, const int ldb_, const int K_, const Sched& S, const Epi& E) {
;     ...
;             PG8_LDA(At, 1, 1); PG8_STAGE(PG8_SB(1, 0), b3, voffB); PG8_STAGE(PG8_SB(1, 1), b3 + hstepB, voffB); PG8_STAGE(PG8_SA(1, 0), a3, voffA);
;             PG8_WAIT_V(8); PG8_WAIT_L(0); PG8_BAR; PG8_MMA(1, 0, At, B0); PG8_MMA(1, 1, At, B1); PG8_BAR; PG8_SCHED;
;         }
;         if constexpr (ALIGN_EPI) { if (wr == 0) PG8_BAR; }
;         E(acc, cur, S, wr, wc, fr, fq);
;     __device__ __forceinline__ void out(const pg8::Unit& u, char*& o, int& ldo, int& kind) const { const int g = u.pm >> 1, cs = u.pm & 1;
;         if (u.pn < 64) { const int b = u.pn >> 3, p0 = (u.pn & 7) * 256; o = (char*)ws + WS_PQT + (((size_t)(b * 2048 + g * 256)) * 4096 + (size_t)cs * 2048 + p0) * 2; ldo = 4096; }
;         else { const int b = u.pn - 64; o = (char*)ws + WS_PQTC + (((size_t)(b * 2048 + g * 256)) * 512 + (size_t)cs * 256) * 2; ldo = 512; }
;         kind = 0; }
	s_mov_b32 m0, s77
	v_lshl_add_u64 v[220:221], v[220:221], 0, s[24:25]
	ds_read_b128 v[188:191], v139 offset:49152
	ds_read_b128 v[192:195], v139 offset:50176
	ds_read_b128 v[196:199], v139 offset:51200
	ds_read_b128 v[200:203], v139 offset:52224
	ds_read_b128 v[204:207], v139 offset:53248
	ds_read_b128 v[208:211], v139 offset:54272
	ds_read_b128 v[212:215], v139 offset:55296
	ds_read_b128 v[216:219], v139 offset:56320
	global_load_lds_dwordx4 v[220:221], off
	v_lshl_add_u64 v[220:221], v[222:223], 0, s[24:25]
	s_mov_b32 m0, s43
	s_nop 0
	global_load_lds_dwordx4 v[220:221], off
	v_lshl_add_u64 v[220:221], v[224:225], 0, s[24:25]
	s_mov_b32 m0, s93
	s_nop 0
	global_load_lds_dwordx4 v[220:221], off
	v_lshl_add_u64 v[220:221], v[226:227], 0, s[24:25]
	s_mov_b32 m0, s42
	s_nop 0
	global_load_lds_dwordx4 v[220:221], off
	v_lshl_add_u64 v[220:221], v[228:229], 0, s[24:25]
	s_mov_b32 m0, s15
	s_nop 0
	global_load_lds_dwordx4 v[220:221], off
	v_lshl_add_u64 v[220:221], v[230:231], 0, s[24:25]
	s_mov_b32 m0, s26
	s_nop 0
	global_load_lds_dwordx4 v[220:221], off
	s_waitcnt vmcnt(8)
	s_waitcnt lgkmcnt(0)
	s_barrier
	s_setprio 1
	s_waitcnt lgkmcnt(0)
	v_mfma_f32_16x16x32_bf16 v[60:63], v[152:155], v[188:191], v[60:63]
	v_mfma_f32_16x16x32_bf16 v[56:59], v[160:163], v[188:191], v[56:59]
	v_mfma_f32_16x16x32_bf16 v[52:55], v[152:155], v[196:199], v[52:55]
	v_mfma_f32_16x16x32_bf16 v[48:51], v[160:163], v[196:199], v[48:51]
	v_mfma_f32_16x16x32_bf16 v[36:39], v[152:155], v[204:207], v[36:39]
	v_mfma_f32_16x16x32_bf16 v[32:35], v[160:163], v[204:207], v[32:35]
	v_mfma_f32_16x16x32_bf16 v[20:23], v[152:155], v[212:215], v[20:23]
	v_mfma_f32_16x16x32_bf16 v[16:19], v[160:163], v[212:215], v[16:19]
	v_mfma_f32_16x16x32_bf16 v[60:63], v[156:159], v[192:195], v[60:63]
	v_mfma_f32_16x16x32_bf16 v[56:59], v[164:167], v[192:195], v[56:59]
	v_mfma_f32_16x16x32_bf16 v[52:55], v[156:159], v[200:203], v[52:55]
	v_mfma_f32_16x16x32_bf16 v[48:51], v[164:167], v[200:203], v[48:51]
	v_mfma_f32_16x16x32_bf16 v[36:39], v[156:159], v[208:211], v[36:39]
	v_mfma_f32_16x16x32_bf16 v[32:35], v[164:167], v[208:211], v[32:35]
	v_mfma_f32_16x16x32_bf16 v[20:23], v[156:159], v[216:219], v[20:23]
	v_mfma_f32_16x16x32_bf16 v[16:19], v[164:167], v[216:219], v[16:19]
	s_setprio 0
	s_setprio 1
	v_mfma_f32_16x16x32_bf16 v[44:47], v[168:171], v[188:191], v[44:47]
	v_mfma_f32_16x16x32_bf16 v[40:43], v[180:183], v[188:191], v[40:43]
	v_mfma_f32_16x16x32_bf16 v[28:31], v[168:171], v[196:199], v[28:31]
	v_mfma_f32_16x16x32_bf16 v[24:27], v[180:183], v[196:199], v[24:27]
	v_mfma_f32_16x16x32_bf16 v[12:15], v[168:171], v[204:207], v[12:15]
	v_mfma_f32_16x16x32_bf16 v[8:11], v[180:183], v[204:207], v[8:11]
	v_mfma_f32_16x16x32_bf16 v[4:7], v[168:171], v[212:215], v[4:7]
	v_mfma_f32_16x16x32_bf16 v[0:3], v[180:183], v[212:215], v[0:3]
	v_mfma_f32_16x16x32_bf16 v[44:47], v[172:175], v[192:195], v[44:47]
	v_mfma_f32_16x16x32_bf16 v[40:43], v[184:187], v[192:195], v[40:43]
	v_mfma_f32_16x16x32_bf16 v[28:31], v[172:175], v[200:203], v[28:31]
	v_mfma_f32_16x16x32_bf16 v[24:27], v[184:187], v[200:203], v[24:27]
	v_mfma_f32_16x16x32_bf16 v[12:15], v[172:175], v[208:211], v[12:15]
	v_mfma_f32_16x16x32_bf16 v[8:11], v[184:187], v[208:211], v[8:11]
	v_mfma_f32_16x16x32_bf16 v[4:7], v[172:175], v[216:219], v[4:7]
	v_mfma_f32_16x16x32_bf16 v[0:3], v[184:187], v[216:219], v[0:3]
	s_setprio 0
	s_barrier
	s_andn2_b64 vcc, exec, s[46:47]
	s_mov_b64 s[48:49], -1
	s_mov_b64 s[46:47], 0
	s_mov_b64 s[50:51], 0x100
	s_cbranch_vccz .LBB0_697
	s_setprio 2
	s_ashr_i32 s43, s75, 1
	s_and_b32 s42, s75, 1
	s_cmp_gt_i32 s74, 63
	s_mov_b64 s[40:41], -1
	s_cbranch_scc0 .LBB0_700
	s_lshl_b32 s4, s74, 11
	s_lshl_b32 s5, s43, 8
	s_add_i32 s4, s4, s5
	s_add_i32 s4, s4, 0xfffe0000
	s_ashr_i32 s5, s4, 31
	s_lshl_b32 s31, s42, 9
	s_lshl_b64 s[4:5], s[4:5], 10
	v_readlane_b32 s17, v254, 2
	s_add_u32 s4, s17, s4
	v_readlane_b32 s17, v254, 3
	s_addc_u32 s5, s17, s5
	s_add_u32 s4, s4, s31
	s_addc_u32 s5, s5, 0
	s_mov_b64 s[40:41], 0

; #define PG8_STAGE(bufoff, gbase, voff) do { _Pragma("unroll") for (int _i = 0; _i < 2; ++_i) \
;         __builtin_amdgcn_global_load_lds((const unsigned*)((const char*)(gbase) + (voff)[_i]), (LAS unsigned*)(lds + (bufoff) + ldsw + _i * 8192), 16, 0, 0); } while (0)
; #define PG8_LDA(dst, b, h) do { _Pragma("unroll") for (int m = 0; m < 4; ++m) _Pragma("unroll") for (int k = 0; k < 2; ++k) dst[m][k] = *(const LAS bf16x8*)(lds + PG8_SA(b, h) + aoff + m * 2048 + k * 1024); } while (0)
; #define PG8_LDB(dst, b, h) do { _Pragma("unroll") for (int n = 0; n < 2; ++n) _Pragma("unroll") for (int k = 0; k < 2; ++k) dst[n][k] = *(const LAS bf16x8*)(lds + PG8_SB(b, h) + boff + n * 2048 + k * 1024); } while (0)
; #define PG8_MMA(ai, bj, At, Bt) do { __builtin_amdgcn_s_setprio(1); _Pragma("unroll") for (int m = 0; m < 4; ++m) _Pragma("unroll") for (int n = 0; n < 2; ++n) _Pragma("unroll") for (int k = 0; k < 2; ++k) \
;         acc[ai][bj][m][n] = __builtin_amdgcn_mfma_f32_16x16x32_bf16(Bt[n][k], At[m][k], acc[ai][bj][m][n], 0, 0, 0); __builtin_amdgcn_s_setprio(0); } while (0)
; #define PG8_WAIT_V(n) asm volatile("s_waitcnt vmcnt(" #n ")" ::: "memory")
; #define PG8_WAIT_L(n) asm volatile("s_waitcnt lgkmcnt(" #n ")" ::: "memory")
; #define PG8_BAR __builtin_amdgcn_s_barrier()
; #define PG8_SCHED __builtin_amdgcn_sched_barrier(0)
; template <class Epi, class Sched, bool ALIGN_EPI>
; __device__ __forceinline__ void gemm_phase(LAS unsigned char* lds, const int wid, const int lda_, const int ldb_, const int K_, const Sched& S, const Epi& E) {
;     ...
;             PG8_LDB(B0, 1, 0); PG8_LDB(B1, 1, 1); PG8_SCHED; PG8_LDA(At, 1, 0); PG8_STAGE(PG8_SA(0, 1), a2 + hstepA, voffA);
;             PG8_WAIT_V(8); PG8_WAIT_L(0); PG8_BAR; PG8_MMA(0, 0, At, B0); PG8_MMA(0, 1, At, B1); PG8_BAR; PG8_SCHED;
;             PG8_LDA(At, 1, 1); PG8_STAGE(PG8_SB(1, 0), b3, voffB); PG8_STAGE(PG8_SB(1, 1), b3 + hstepB, voffB); PG8_STAGE(PG8_SA(1, 0), a3, voffA);
;             PG8_WAIT_V(8); PG8_WAIT_L(0); PG8_BAR; PG8_MMA(1, 0, At, B0); PG8_MMA(1, 1, At, B1); PG8_BAR; PG8_SCHED;
.Lgemm_join_883:
	s_add_i32 s17, 0, 0x18000
	v_add_u32_e32 v141, s17, v135
	s_add_i32 s27, 0, 0x1c000
	ds_read_b128 v[160:163], v141
	ds_read_b128 v[164:167], v141 offset:1024
	ds_read_b128 v[168:171], v141 offset:2048
	ds_read_b128 v[172:175], v141 offset:3072
	v_add_u32_e32 v141, s27, v135
	ds_read_b128 v[180:183], v141
	ds_read_b128 v[184:187], v141 offset:1024
	ds_read_b128 v[188:191], v141 offset:2048
	ds_read_b128 v[192:195], v141 offset:3072
	s_add_u32 s42, s50, s0
	s_addc_u32 s43, s51, s1
	s_mov_b32 m0, s7
	v_lshl_add_u64 v[248:249], s[42:43], 0, v[128:129]
	ds_read_b128 v[196:199], v139 offset:32768
	ds_read_b128 v[200:203], v139 offset:33792
	ds_read_b128 v[204:207], v139 offset:34816
	ds_read_b128 v[208:211], v139 offset:35840
	ds_read_b128 v[212:215], v139 offset:36864
	ds_read_b128 v[216:219], v139 offset:37888
	ds_read_b128 v[220:223], v139 offset:38912
	ds_read_b128 v[224:227], v139 offset:39936
	global_load_lds_dwordx4 v[248:249], off
	v_lshl_add_u64 v[248:249], s[42:43], 0, v[130:131]
	s_mov_b32 m0, s14
	s_nop 0
	global_load_lds_dwordx4 v[248:249], off
	s_waitcnt vmcnt(8)
	s_waitcnt lgkmcnt(0)
	s_barrier
	s_setprio 1
	s_waitcnt lgkmcnt(0)
	v_mfma_f32_16x16x32_bf16 v[124:127], v[160:163], v[196:199], v[124:127]
	v_mfma_f32_16x16x32_bf16 v[120:123], v[168:171], v[196:199], v[120:123]
	v_mfma_f32_16x16x32_bf16 v[116:119], v[160:163], v[204:207], v[116:119]
	v_mfma_f32_16x16x32_bf16 v[112:115], v[168:171], v[204:207], v[112:115]
	v_mfma_f32_16x16x32_bf16 v[100:103], v[160:163], v[212:215], v[100:103]
	v_mfma_f32_16x16x32_bf16 v[96:99], v[168:171], v[212:215], v[96:99]
	v_mfma_f32_16x16x32_bf16 v[84:87], v[160:163], v[220:223], v[84:87]
	v_mfma_f32_16x16x32_bf16 v[80:83], v[168:171], v[220:223], v[80:83]
	v_mfma_f32_16x16x32_bf16 v[124:127], v[164:167], v[200:203], v[124:127]
	v_mfma_f32_16x16x32_bf16 v[120:123], v[172:175], v[200:203], v[120:123]
	v_mfma_f32_16x16x32_bf16 v[116:119], v[164:167], v[208:211], v[116:119]
	v_mfma_f32_16x16x32_bf16 v[112:115], v[172:175], v[208:211], v[112:115]
	v_mfma_f32_16x16x32_bf16 v[100:103], v[164:167], v[216:219], v[100:103]
	v_mfma_f32_16x16x32_bf16 v[96:99], v[172:175], v[216:219], v[96:99]
	v_mfma_f32_16x16x32_bf16 v[84:87], v[164:167], v[224:227], v[84:87]
	v_mfma_f32_16x16x32_bf16 v[80:83], v[172:175], v[224:227], v[80:83]
	s_setprio 0
	s_setprio 1
	v_mfma_f32_16x16x32_bf16 v[108:111], v[180:183], v[196:199], v[108:111]
	v_mfma_f32_16x16x32_bf16 v[104:107], v[188:191], v[196:199], v[104:107]
	v_mfma_f32_16x16x32_bf16 v[92:95], v[180:183], v[204:207], v[92:95]
	v_mfma_f32_16x16x32_bf16 v[88:91], v[188:191], v[204:207], v[88:91]
	v_mfma_f32_16x16x32_bf16 v[76:79], v[180:183], v[212:215], v[76:79]
	v_mfma_f32_16x16x32_bf16 v[72:75], v[188:191], v[212:215], v[72:75]
	v_mfma_f32_16x16x32_bf16 v[68:71], v[180:183], v[220:223], v[68:71]
	v_mfma_f32_16x16x32_bf16 v[64:67], v[188:191], v[220:223], v[64:67]
	v_mfma_f32_16x16x32_bf16 v[108:111], v[184:187], v[200:203], v[108:111]
	v_mfma_f32_16x16x32_bf16 v[104:107], v[192:195], v[200:203], v[104:107]
	v_mfma_f32_16x16x32_bf16 v[92:95], v[184:187], v[208:211], v[92:95]
	v_mfma_f32_16x16x32_bf16 v[88:91], v[192:195], v[208:211], v[88:91]
	v_mfma_f32_16x16x32_bf16 v[76:79], v[184:187], v[216:219], v[76:79]
	v_mfma_f32_16x16x32_bf16 v[72:75], v[192:195], v[216:219], v[72:75]
	v_mfma_f32_16x16x32_bf16 v[68:71], v[184:187], v[224:227], v[68:71]
	v_mfma_f32_16x16x32_bf16 v[64:67], v[192:195], v[224:227], v[64:67]
	s_setprio 0
	s_barrier
	s_add_i32 s17, s17, s3
	v_lshl_add_u64 v[228:229], v[228:229], 0, s[24:25]
	s_mov_b32 m0, s17
	ds_read_b128 v[196:199], v139 offset:49152
	ds_read_b128 v[200:203], v139 offset:50176
	ds_read_b128 v[204:207], v139 offset:51200
	ds_read_b128 v[208:211], v139 offset:52224
	ds_read_b128 v[212:215], v139 offset:53248
	ds_read_b128 v[216:219], v139 offset:54272
	ds_read_b128 v[220:223], v139 offset:55296
	ds_read_b128 v[224:227], v139 offset:56320
	global_load_lds_dwordx4 v[228:229], off
	v_lshl_add_u64 v[228:229], v[230:231], 0, s[24:25]
	s_add_i32 m0, s17, 0x2000
	s_add_i32 s17, s27, s3
	global_load_lds_dwordx4 v[228:229], off
	v_lshl_add_u64 v[228:229], v[232:233], 0, s[24:25]
	s_mov_b32 m0, s17
	s_nop 0
	global_load_lds_dwordx4 v[228:229], off
	v_lshl_add_u64 v[228:229], v[234:235], 0, s[24:25]
	s_add_i32 m0, s17, 0x2000
	s_nop 0
	global_load_lds_dwordx4 v[228:229], off
	v_lshl_add_u64 v[228:229], v[236:237], 0, s[24:25]
	s_mov_b32 m0, s15
	s_nop 0
	global_load_lds_dwordx4 v[228:229], off
	v_lshl_add_u64 v[228:229], v[246:247], 0, s[24:25]
	s_mov_b32 m0, s26
	s_nop 0
	global_load_lds_dwordx4 v[228:229], off
	s_waitcnt vmcnt(8)
	s_waitcnt lgkmcnt(0)
	s_barrier
; #define PG8_MMA(ai, bj, At, Bt) do { __builtin_amdgcn_s_setprio(1); _Pragma("unroll") for (int m = 0; m < 4; ++m) _Pragma("unroll") for (int n = 0; n < 2; ++n) _Pragma("unroll") for (int k = 0; k < 2; ++k) \
;         acc[ai][bj][m][n] = __builtin_amdgcn_mfma_f32_16x16x32_bf16(Bt[n][k], At[m][k], acc[ai][bj][m][n], 0, 0, 0); __builtin_amdgcn_s_setprio(0); } while (0)
; #define PG8_WAIT_V(n) asm volatile("s_waitcnt vmcnt(" #n ")" ::: "memory")
; #define PG8_WAIT_L(n) asm volatile("s_waitcnt lgkmcnt(" #n ")" ::: "memory")
; #define PG8_BAR __builtin_amdgcn_s_barrier()
; #define PG8_SCHED __builtin_amdgcn_sched_barrier(0)
; template <class Epi, class Sched, bool ALIGN_EPI>
; __device__ __forceinline__ void gemm_phase(LAS unsigned char* lds, const int wid, const int lda_, const int ldb_, const int K_, const Sched& S, const Epi& E) {
;     ...
;             PG8_WAIT_V(8); PG8_WAIT_L(0); PG8_BAR; PG8_MMA(1, 0, At, B0); PG8_MMA(1, 1, At, B1); PG8_BAR; PG8_SCHED;
;         }
	s_setprio 1
	s_waitcnt lgkmcnt(0)
	v_mfma_f32_16x16x32_bf16 v[60:63], v[160:163], v[196:199], v[60:63]
	v_mfma_f32_16x16x32_bf16 v[56:59], v[168:171], v[196:199], v[56:59]
	v_mfma_f32_16x16x32_bf16 v[52:55], v[160:163], v[204:207], v[52:55]
	v_mfma_f32_16x16x32_bf16 v[48:51], v[168:171], v[204:207], v[48:51]
	v_mfma_f32_16x16x32_bf16 v[36:39], v[160:163], v[212:215], v[36:39]
	v_mfma_f32_16x16x32_bf16 v[32:35], v[168:171], v[212:215], v[32:35]
	v_mfma_f32_16x16x32_bf16 v[20:23], v[160:163], v[220:223], v[20:23]
	v_mfma_f32_16x16x32_bf16 v[16:19], v[168:171], v[220:223], v[16:19]
	v_mfma_f32_16x16x32_bf16 v[60:63], v[164:167], v[200:203], v[60:63]
	v_mfma_f32_16x16x32_bf16 v[56:59], v[172:175], v[200:203], v[56:59]
	v_mfma_f32_16x16x32_bf16 v[52:55], v[164:167], v[208:211], v[52:55]
	v_mfma_f32_16x16x32_bf16 v[48:51], v[172:175], v[208:211], v[48:51]
	v_mfma_f32_16x16x32_bf16 v[36:39], v[164:167], v[216:219], v[36:39]
	v_mfma_f32_16x16x32_bf16 v[32:35], v[172:175], v[216:219], v[32:35]
	v_mfma_f32_16x16x32_bf16 v[20:23], v[164:167], v[224:227], v[20:23]
	v_mfma_f32_16x16x32_bf16 v[16:19], v[172:175], v[224:227], v[16:19]
	s_setprio 0
	s_setprio 1
	v_mfma_f32_16x16x32_bf16 v[44:47], v[180:183], v[196:199], v[44:47]
	v_mfma_f32_16x16x32_bf16 v[40:43], v[188:191], v[196:199], v[40:43]
	v_mfma_f32_16x16x32_bf16 v[28:31], v[180:183], v[204:207], v[28:31]
	v_mfma_f32_16x16x32_bf16 v[24:27], v[188:191], v[204:207], v[24:27]
	v_mfma_f32_16x16x32_bf16 v[12:15], v[180:183], v[212:215], v[12:15]
	v_mfma_f32_16x16x32_bf16 v[8:11], v[188:191], v[212:215], v[8:11]
	v_mfma_f32_16x16x32_bf16 v[4:7], v[180:183], v[220:223], v[4:7]
	v_mfma_f32_16x16x32_bf16 v[0:3], v[188:191], v[220:223], v[0:3]
	v_mfma_f32_16x16x32_bf16 v[44:47], v[184:187], v[200:203], v[44:47]
	v_mfma_f32_16x16x32_bf16 v[40:43], v[192:195], v[200:203], v[40:43]
	v_mfma_f32_16x16x32_bf16 v[28:31], v[184:187], v[208:211], v[28:31]
	v_mfma_f32_16x16x32_bf16 v[24:27], v[192:195], v[208:211], v[24:27]
	v_mfma_f32_16x16x32_bf16 v[12:15], v[184:187], v[216:219], v[12:15]
	v_mfma_f32_16x16x32_bf16 v[8:11], v[192:195], v[216:219], v[8:11]
	v_mfma_f32_16x16x32_bf16 v[4:7], v[184:187], v[224:227], v[4:7]
	v_mfma_f32_16x16x32_bf16 v[0:3], v[192:195], v[224:227], v[0:3]
	s_setprio 0
	s_barrier
	s_add_i32 s73, s73, 2
	s_add_u32 s48, s48, 0x100
	s_addc_u32 s49, s49, 0
	s_cmp_gt_u32 s73, 5
	s_cbranch_scc0 .LBB0_883
; __device__ __forceinline__ unsigned cvt_pk_bf16(float lo, float hi) { const f32x2 v = {lo, hi}; return __builtin_bit_cast(unsigned, __builtin_convertvector(v, bf16x2_t)); }
;     template <class Sched> __device__ __forceinline__ void operator()(const f32x4 (&acc)[2][2][4][2], const Unit& u, const Sched& S, int wr, int wc, int fr, int fq) const {
;         const int rl0 = wr * 64 + fr, cl0 = wc * 32 + 8 * fq;
;         char* uo; int ldo, kind; S.out(u, uo, ldo, kind);
;         asm volatile("" : "+s"(ldo));
;         if (kind == 0) {
;             bf16_t* base = (bf16_t*)uo;
; #pragma unroll
;             for (int ai = 0; ai < 2; ++ai)
; #pragma unroll
;                 for (int m = 0; m < 4; ++m) { bf16_t* rowp = base + (size_t)(rl0 + ai * HALF + m * 16) * ldo + cl0;
; #pragma unroll
;                     for (int bj = 0; bj < 2; ++bj) { const f32x4 v0 = acc[ai][bj][m][0], v1 = acc[ai][bj][m][1];
;                         u32x4 w; w.x = cvt_pk_bf16(v0[0], v0[1]); w.y = cvt_pk_bf16(v0[2], v0[3]); w.z = cvt_pk_bf16(v1[0], v1[1]); w.w = cvt_pk_bf16(v1[2], v1[3]);
;                         *(u32x4*)(rowp + bj * HALF) = w; } }
;         if (u.pm < 64) { o = (char*)ws + WS_F + (((size_t)((u.pm >> 3) * 2048 + (u.pm & 7))) * D + (size_t)u.pn * 256) * 2; ldo = 8 * D; }
;         else { o = (char*)ws + WS_F + (((size_t)(MLAT + (u.pm - 64) * 256)) * D + (size_t)u.pn * 256) * 2; ldo = D; } }
	s_setprio 2
	s_lshl_b32 s4, s41, 8
	s_and_b32 s5, s4, 0xfffff800
	s_and_b32 s17, s41, 7
	s_or_b32 s17, s5, s17
	s_ashr_i32 s5, s17, 31
	s_cmp_lt_i32 s41, 64
	s_cselect_b32 s4, s17, s4
	s_movk_i32 s17, 0x800
	s_cselect_b32 s5, s5, 0
	s_cselect_b32 s17, 0x4000, s17
	s_ashr_i32 s41, s40, 31
	s_lshl_b64 s[40:41], s[40:41], 9
	s_lshl_b64 s[4:5], s[4:5], 12
	v_readlane_b32 s27, v254, 19
	s_add_u32 s4, s27, s4
	v_readlane_b32 s27, v254, 20
	s_addc_u32 s5, s27, s5
	s_add_u32 s4, s4, s40
	s_addc_u32 s5, s5, s41
	v_lshl_add_u64 v[156:157], v[136:137], 1, s[4:5]
	v_mad_i64_i32 v[158:159], s[4:5], s17, v134, 0
	v_lshl_add_u64 v[158:159], v[158:159], 1, v[156:157]
	v_cvt_pk_bf16_f32 v108, v108, v109
	v_cvt_pk_bf16_f32 v109, v110, v111
	v_cvt_pk_bf16_f32 v110, v104, v105
	v_cvt_pk_bf16_f32 v111, v106, v107
	v_mad_i64_i32 v[104:105], s[4:5], s17, v138, 0
	v_cvt_pk_bf16_f32 v124, v124, v125
	v_cvt_pk_bf16_f32 v125, v126, v127
	v_cvt_pk_bf16_f32 v126, v120, v121
	v_cvt_pk_bf16_f32 v127, v122, v123
	global_store_dwordx4 v[158:159], v[108:111], off offset:256
	v_cvt_pk_bf16_f32 v92, v92, v93
	v_cvt_pk_bf16_f32 v93, v94, v95
	v_lshl_add_u64 v[108:109], v[104:105], 1, v[156:157]
	v_cvt_pk_bf16_f32 v94, v88, v89
	v_cvt_pk_bf16_f32 v95, v90, v91
	v_mad_i64_i32 v[88:89], s[4:5], s17, v140, 0
	global_store_dwordx4 v[158:159], v[124:127], off
	v_cvt_pk_bf16_f32 v104, v116, v117
	v_cvt_pk_bf16_f32 v105, v118, v119
	v_cvt_pk_bf16_f32 v106, v112, v113
	v_cvt_pk_bf16_f32 v107, v114, v115
	global_store_dwordx4 v[108:109], v[92:95], off offset:256
	v_cvt_pk_bf16_f32 v76, v76, v77
	v_cvt_pk_bf16_f32 v77, v78, v79
	v_lshl_add_u64 v[92:93], v[88:89], 1, v[156:157]
	v_cvt_pk_bf16_f32 v78, v72, v73
	v_cvt_pk_bf16_f32 v79, v74, v75
	v_mad_i64_i32 v[72:73], s[4:5], s17, v142, 0
	v_cvt_pk_bf16_f32 v68, v68, v69
	v_cvt_pk_bf16_f32 v69, v70, v71
	v_cvt_pk_bf16_f32 v70, v64, v65
	v_mad_i64_i32 v[64:65], s[4:5], s17, v144, 0
	global_store_dwordx4 v[108:109], v[104:107], off
	v_cvt_pk_bf16_f32 v88, v100, v101
	v_cvt_pk_bf16_f32 v89, v102, v103
	v_cvt_pk_bf16_f32 v90, v96, v97
	v_cvt_pk_bf16_f32 v91, v98, v99
	global_store_dwordx4 v[92:93], v[76:79], off offset:256
	v_cvt_pk_bf16_f32 v74, v80, v81
	v_cvt_pk_bf16_f32 v75, v82, v83
	v_lshl_add_u64 v[76:77], v[72:73], 1, v[156:157]
	v_cvt_pk_bf16_f32 v72, v84, v85
	v_cvt_pk_bf16_f32 v73, v86, v87
	v_cvt_pk_bf16_f32 v71, v66, v67
	v_lshl_add_u64 v[64:65], v[64:65], 1, v[156:157]
	v_cvt_pk_bf16_f32 v44, v44, v45
	v_cvt_pk_bf16_f32 v45, v46, v47
	v_cvt_pk_bf16_f32 v46, v40, v41
	v_cvt_pk_bf16_f32 v47, v42, v43
	v_mad_i64_i32 v[40:41], s[4:5], s17, v146, 0
	global_store_dwordx4 v[92:93], v[88:91], off
	global_store_dwordx4 v[76:77], v[72:75], off
	global_store_dwordx4 v[76:77], v[68:71], off offset:256
	v_cvt_pk_bf16_f32 v60, v60, v61
	v_cvt_pk_bf16_f32 v61, v62, v63
	v_cvt_pk_bf16_f32 v62, v56, v57
	v_cvt_pk_bf16_f32 v63, v58, v59
	global_store_dwordx4 v[64:65], v[44:47], off offset:256
	v_cvt_pk_bf16_f32 v28, v28, v29
	v_cvt_pk_bf16_f32 v29, v30, v31
	v_lshl_add_u64 v[44:45], v[40:41], 1, v[156:157]
	v_cvt_pk_bf16_f32 v30, v24, v25
	v_cvt_pk_bf16_f32 v31, v26, v27
	v_mad_i64_i32 v[24:25], s[4:5], s17, v148, 0
	global_store_dwordx4 v[64:65], v[60:63], off
	v_cvt_pk_bf16_f32 v40, v52, v53
	v_cvt_pk_bf16_f32 v41, v54, v55
	v_cvt_pk_bf16_f32 v42, v48, v49
	v_cvt_pk_bf16_f32 v43, v50, v51
	global_store_dwordx4 v[44:45], v[28:31], off offset:256
	v_cvt_pk_bf16_f32 v12, v12, v13
	v_cvt_pk_bf16_f32 v13, v14, v15
	v_lshl_add_u64 v[28:29], v[24:25], 1, v[156:157]
	v_cvt_pk_bf16_f32 v14, v8, v9
	v_cvt_pk_bf16_f32 v15, v10, v11
	v_mad_i64_i32 v[8:9], s[4:5], s17, v150, 0
	global_store_dwordx4 v[44:45], v[40:43], off
	v_cvt_pk_bf16_f32 v24, v36, v37
	v_cvt_pk_bf16_f32 v25, v38, v39
	v_cvt_pk_bf16_f32 v26, v32, v33
	v_cvt_pk_bf16_f32 v27, v34, v35
	global_store_dwordx4 v[28:29], v[12:15], off offset:256
	v_cvt_pk_bf16_f32 v10, v16, v17
	v_cvt_pk_bf16_f32 v11, v18, v19
	v_lshl_add_u64 v[12:13], v[8:9], 1, v[156:157]
	v_cvt_pk_bf16_f32 v8, v20, v21
	v_cvt_pk_bf16_f32 v9, v22, v23
	v_cvt_pk_bf16_f32 v4, v4, v5
	v_cvt_pk_bf16_f32 v5, v6, v7
	v_cvt_pk_bf16_f32 v6, v0, v1
	v_cvt_pk_bf16_f32 v7, v2, v3
	s_and_b64 vcc, exec, s[36:37]
	s_mov_b32 s40, s30
	s_mov_b32 s41, s34
	s_mov_b64 s[48:49], s[38:39]
	s_mov_b64 s[46:47], s[44:45]
	global_store_dwordx4 v[28:29], v[24:27], off
	global_store_dwordx4 v[12:13], v[8:11], off
	global_store_dwordx4 v[12:13], v[4:7], off offset:256
	s_cbranch_vccz .LBB0_868
	v_readlane_b32 s0, v253, 1
	s_waitcnt vmcnt(0)
	v_readlane_b32 s1, v253, 2
	v_readlane_b32 s72, v255, 28
	s_andn2_b64 vcc, exec, s[0:1]
	v_readlane_b32 s73, v255, 29
	s_cbranch_vccnz .LBB0_887
	s_barrier

; #define PG8_STAGE(bufoff, gbase, voff) do { _Pragma("unroll") for (int _i = 0; _i < 2; ++_i) \
;         __builtin_amdgcn_global_load_lds((const unsigned*)((const char*)(gbase) + (voff)[_i]), (LAS unsigned*)(lds + (bufoff) + ldsw + _i * 8192), 16, 0, 0); } while (0)
; #define PG8_LDA(dst, b, h) do { _Pragma("unroll") for (int m = 0; m < 4; ++m) _Pragma("unroll") for (int k = 0; k < 2; ++k) dst[m][k] = *(const LAS bf16x8*)(lds + PG8_SA(b, h) + aoff + m * 2048 + k * 1024); } while (0)
; #define PG8_LDB(dst, b, h) do { _Pragma("unroll") for (int n = 0; n < 2; ++n) _Pragma("unroll") for (int k = 0; k < 2; ++k) dst[n][k] = *(const LAS bf16x8*)(lds + PG8_SB(b, h) + boff + n * 2048 + k * 1024); } while (0)
; #define PG8_MMA(ai, bj, At, Bt) do { __builtin_amdgcn_s_setprio(1); _Pragma("unroll") for (int m = 0; m < 4; ++m) _Pragma("unroll") for (int n = 0; n < 2; ++n) _Pragma("unroll") for (int k = 0; k < 2; ++k) \
;         acc[ai][bj][m][n] = __builtin_amdgcn_mfma_f32_16x16x32_bf16(Bt[n][k], At[m][k], acc[ai][bj][m][n], 0, 0, 0); __builtin_amdgcn_s_setprio(0); } while (0)
; #define PG8_WAIT_V(n) asm volatile("s_waitcnt vmcnt(" #n ")" ::: "memory")
; #define PG8_WAIT_L(n) asm volatile("s_waitcnt lgkmcnt(" #n ")" ::: "memory")
; #define PG8_BAR __builtin_amdgcn_s_barrier()
; #define PG8_SCHED __builtin_amdgcn_sched_barrier(0)
; template <class Epi, class Sched, bool ALIGN_EPI>
; __device__ __forceinline__ void gemm_phase(LAS unsigned char* lds, const int wid, const int lda_, const int ldb_, const int K_, const Sched& S, const Epi& E) {
;     ...
;             PG8_LDB(B0, 1, 0); PG8_LDB(B1, 1, 1); PG8_SCHED; PG8_LDA(At, 1, 0); PG8_STAGE(PG8_SA(0, 1), a2 + hstepA, voffA);
;             PG8_WAIT_V(8); PG8_WAIT_L(0); PG8_BAR; PG8_MMA(0, 0, At, B0); PG8_MMA(0, 1, At, B1); PG8_BAR; PG8_SCHED;
.Lgemm_join_962:
	s_add_i32 s17, 0, 0x18000
	v_add_u32_e32 v141, s17, v135
	s_add_i32 s27, 0, 0x1c000
	ds_read_b128 v[156:159], v141
	ds_read_b128 v[160:163], v141 offset:1024
	ds_read_b128 v[164:167], v141 offset:2048
	ds_read_b128 v[168:171], v141 offset:3072
	v_add_u32_e32 v141, s27, v135
	ds_read_b128 v[172:175], v141
	ds_read_b128 v[180:183], v141 offset:1024
	ds_read_b128 v[184:187], v141 offset:2048
	ds_read_b128 v[188:191], v141 offset:3072
	s_add_u32 s42, s96, s0
	s_addc_u32 s43, s97, s1
	s_mov_b32 m0, s15
	v_lshl_add_u64 v[236:237], s[42:43], 0, v[132:133]
	ds_read_b128 v[192:195], v139 offset:32768
	ds_read_b128 v[196:199], v139 offset:33792
	ds_read_b128 v[200:203], v139 offset:34816
	ds_read_b128 v[204:207], v139 offset:35840
	ds_read_b128 v[208:211], v139 offset:36864
	ds_read_b128 v[212:215], v139 offset:37888
	ds_read_b128 v[216:219], v139 offset:38912
	ds_read_b128 v[220:223], v139 offset:39936
	global_load_lds_dwordx4 v[236:237], off
	v_lshl_add_u64 v[236:237], s[42:43], 0, v[130:131]
	s_mov_b32 m0, s26
	s_nop 0
	global_load_lds_dwordx4 v[236:237], off
	s_waitcnt vmcnt(8)
	s_waitcnt lgkmcnt(0)
	s_barrier
	s_setprio 1
	s_waitcnt lgkmcnt(0)
	v_mfma_f32_16x16x32_bf16 v[124:127], v[156:159], v[192:195], v[124:127]
	v_mfma_f32_16x16x32_bf16 v[120:123], v[164:167], v[192:195], v[120:123]
	v_mfma_f32_16x16x32_bf16 v[116:119], v[156:159], v[200:203], v[116:119]
	v_mfma_f32_16x16x32_bf16 v[112:115], v[164:167], v[200:203], v[112:115]
	v_mfma_f32_16x16x32_bf16 v[100:103], v[156:159], v[208:211], v[100:103]
	v_mfma_f32_16x16x32_bf16 v[96:99], v[164:167], v[208:211], v[96:99]
	v_mfma_f32_16x16x32_bf16 v[84:87], v[156:159], v[216:219], v[84:87]
	v_mfma_f32_16x16x32_bf16 v[80:83], v[164:167], v[216:219], v[80:83]
	v_mfma_f32_16x16x32_bf16 v[124:127], v[160:163], v[196:199], v[124:127]
	v_mfma_f32_16x16x32_bf16 v[120:123], v[168:171], v[196:199], v[120:123]
	v_mfma_f32_16x16x32_bf16 v[116:119], v[160:163], v[204:207], v[116:119]
	v_mfma_f32_16x16x32_bf16 v[112:115], v[168:171], v[204:207], v[112:115]
	v_mfma_f32_16x16x32_bf16 v[100:103], v[160:163], v[212:215], v[100:103]
	v_mfma_f32_16x16x32_bf16 v[96:99], v[168:171], v[212:215], v[96:99]
	v_mfma_f32_16x16x32_bf16 v[84:87], v[160:163], v[220:223], v[84:87]
	v_mfma_f32_16x16x32_bf16 v[80:83], v[168:171], v[220:223], v[80:83]
	s_setprio 0
	s_setprio 1
	v_mfma_f32_16x16x32_bf16 v[108:111], v[172:175], v[192:195], v[108:111]
	v_mfma_f32_16x16x32_bf16 v[104:107], v[184:187], v[192:195], v[104:107]
	v_mfma_f32_16x16x32_bf16 v[92:95], v[172:175], v[200:203], v[92:95]
	v_mfma_f32_16x16x32_bf16 v[88:91], v[184:187], v[200:203], v[88:91]
	v_mfma_f32_16x16x32_bf16 v[76:79], v[172:175], v[208:211], v[76:79]
	v_mfma_f32_16x16x32_bf16 v[72:75], v[184:187], v[208:211], v[72:75]
	v_mfma_f32_16x16x32_bf16 v[68:71], v[172:175], v[216:219], v[68:71]
	v_mfma_f32_16x16x32_bf16 v[64:67], v[184:187], v[216:219], v[64:67]
	v_mfma_f32_16x16x32_bf16 v[108:111], v[180:183], v[196:199], v[108:111]
	v_mfma_f32_16x16x32_bf16 v[104:107], v[188:191], v[196:199], v[104:107]
	v_mfma_f32_16x16x32_bf16 v[92:95], v[180:183], v[204:207], v[92:95]
	v_mfma_f32_16x16x32_bf16 v[88:91], v[188:191], v[204:207], v[88:91]
	v_mfma_f32_16x16x32_bf16 v[76:79], v[180:183], v[212:215], v[76:79]
	v_mfma_f32_16x16x32_bf16 v[72:75], v[188:191], v[212:215], v[72:75]
	v_mfma_f32_16x16x32_bf16 v[68:71], v[180:183], v[220:223], v[68:71]
	v_mfma_f32_16x16x32_bf16 v[64:67], v[188:191], v[220:223], v[64:67]
	s_setprio 0
	s_barrier
; #define PG8_STAGE(bufoff, gbase, voff) do { _Pragma("unroll") for (int _i = 0; _i < 2; ++_i) \
;         __builtin_amdgcn_global_load_lds((const unsigned*)((const char*)(gbase) + (voff)[_i]), (LAS unsigned*)(lds + (bufoff) + ldsw + _i * 8192), 16, 0, 0); } while (0)
; #define PG8_LDA(dst, b, h) do { _Pragma("unroll") for (int m = 0; m < 4; ++m) _Pragma("unroll") for (int k = 0; k < 2; ++k) dst[m][k] = *(const LAS bf16x8*)(lds + PG8_SA(b, h) + aoff + m * 2048 + k * 1024); } while (0)
; #define PG8_MMA(ai, bj, At, Bt) do { __builtin_amdgcn_s_setprio(1); _Pragma("unroll") for (int m = 0; m < 4; ++m) _Pragma("unroll") for (int n = 0; n < 2; ++n) _Pragma("unroll") for (int k = 0; k < 2; ++k) \
;         acc[ai][bj][m][n] = __builtin_amdgcn_mfma_f32_16x16x32_bf16(Bt[n][k], At[m][k], acc[ai][bj][m][n], 0, 0, 0); __builtin_amdgcn_s_setprio(0); } while (0)
; #define PG8_WAIT_V(n) asm volatile("s_waitcnt vmcnt(" #n ")" ::: "memory")
; #define PG8_WAIT_L(n) asm volatile("s_waitcnt lgkmcnt(" #n ")" ::: "memory")
; #define PG8_BAR __builtin_amdgcn_s_barrier()
; #define PG8_SCHED __builtin_amdgcn_sched_barrier(0)
; template <class Epi, class Sched, bool ALIGN_EPI>
; __device__ __forceinline__ void gemm_phase(LAS unsigned char* lds, const int wid, const int lda_, const int ldb_, const int K_, const Sched& S, const Epi& E) {
;     ...
;             PG8_LDA(At, 1, 1); PG8_STAGE(PG8_SB(1, 0), b3, voffB); PG8_STAGE(PG8_SB(1, 1), b3 + hstepB, voffB); PG8_STAGE(PG8_SA(1, 0), a3, voffA);
;             PG8_WAIT_V(8); PG8_WAIT_L(0); PG8_BAR; PG8_MMA(1, 0, At, B0); PG8_MMA(1, 1, At, B1); PG8_BAR; PG8_SCHED;
;         }
;         if constexpr (ALIGN_EPI) { if (wr == 0) PG8_BAR; }
;         E(acc, cur, S, wr, wc, fr, fq);
;         if (!has_next) break;
;     __device__ __forceinline__ void out(const pg8::Unit& u, char*& o, int& ldo, int& kind) const { ldo = D;
;         if (u.kq < 0) { o = (char*)ws + YOFF + ((size_t)u.pm * 256 * D + (size_t)u.pn * 256) * 2; kind = 0; }
;         else { o = (char*)ws + WS_PART + (((size_t)u.kq * MCTX + (size_t)(u.pm - 64) * 256) * D + (size_t)u.pn * 256) * 2; kind = 0; } }
	s_add_i32 s17, s17, s3
	v_lshl_add_u64 v[224:225], v[224:225], 0, s[24:25]
	s_mov_b32 m0, s17
	ds_read_b128 v[192:195], v139 offset:49152
	ds_read_b128 v[196:199], v139 offset:50176
	ds_read_b128 v[200:203], v139 offset:51200
	ds_read_b128 v[204:207], v139 offset:52224
	ds_read_b128 v[208:211], v139 offset:53248
	ds_read_b128 v[212:215], v139 offset:54272
	ds_read_b128 v[216:219], v139 offset:55296
	ds_read_b128 v[220:223], v139 offset:56320
	global_load_lds_dwordx4 v[224:225], off
	v_lshl_add_u64 v[224:225], v[226:227], 0, s[24:25]
	s_add_i32 m0, s17, 0x2000
	s_add_i32 s17, s27, s3
	global_load_lds_dwordx4 v[224:225], off
	v_lshl_add_u64 v[224:225], v[228:229], 0, s[24:25]
	s_mov_b32 m0, s17
	s_nop 0
	global_load_lds_dwordx4 v[224:225], off
	v_lshl_add_u64 v[224:225], v[230:231], 0, s[24:25]
	s_add_i32 m0, s17, 0x2000
	s_nop 0
	global_load_lds_dwordx4 v[224:225], off
	v_lshl_add_u64 v[224:225], v[232:233], 0, s[24:25]
	s_mov_b32 m0, s72
	s_nop 0
	global_load_lds_dwordx4 v[224:225], off
	v_lshl_add_u64 v[224:225], v[234:235], 0, s[24:25]
	s_mov_b32 m0, s73
	s_nop 0
	global_load_lds_dwordx4 v[224:225], off
	s_waitcnt vmcnt(8)
	s_waitcnt lgkmcnt(0)
	s_barrier
	s_setprio 1
	s_waitcnt lgkmcnt(0)
	v_mfma_f32_16x16x32_bf16 v[60:63], v[156:159], v[192:195], v[60:63]
	v_mfma_f32_16x16x32_bf16 v[56:59], v[164:167], v[192:195], v[56:59]
	v_mfma_f32_16x16x32_bf16 v[52:55], v[156:159], v[200:203], v[52:55]
	v_mfma_f32_16x16x32_bf16 v[48:51], v[164:167], v[200:203], v[48:51]
	v_mfma_f32_16x16x32_bf16 v[36:39], v[156:159], v[208:211], v[36:39]
	v_mfma_f32_16x16x32_bf16 v[32:35], v[164:167], v[208:211], v[32:35]
	v_mfma_f32_16x16x32_bf16 v[20:23], v[156:159], v[216:219], v[20:23]
	v_mfma_f32_16x16x32_bf16 v[16:19], v[164:167], v[216:219], v[16:19]
	v_mfma_f32_16x16x32_bf16 v[60:63], v[160:163], v[196:199], v[60:63]
	v_mfma_f32_16x16x32_bf16 v[56:59], v[168:171], v[196:199], v[56:59]
	v_mfma_f32_16x16x32_bf16 v[52:55], v[160:163], v[204:207], v[52:55]
	v_mfma_f32_16x16x32_bf16 v[48:51], v[168:171], v[204:207], v[48:51]
	v_mfma_f32_16x16x32_bf16 v[36:39], v[160:163], v[212:215], v[36:39]
	v_mfma_f32_16x16x32_bf16 v[32:35], v[168:171], v[212:215], v[32:35]
	v_mfma_f32_16x16x32_bf16 v[20:23], v[160:163], v[220:223], v[20:23]
	v_mfma_f32_16x16x32_bf16 v[16:19], v[168:171], v[220:223], v[16:19]
	s_setprio 0
	s_setprio 1
	v_mfma_f32_16x16x32_bf16 v[44:47], v[172:175], v[192:195], v[44:47]
	v_mfma_f32_16x16x32_bf16 v[40:43], v[184:187], v[192:195], v[40:43]
	v_mfma_f32_16x16x32_bf16 v[28:31], v[172:175], v[200:203], v[28:31]
	v_mfma_f32_16x16x32_bf16 v[24:27], v[184:187], v[200:203], v[24:27]
	v_mfma_f32_16x16x32_bf16 v[12:15], v[172:175], v[208:211], v[12:15]
	v_mfma_f32_16x16x32_bf16 v[8:11], v[184:187], v[208:211], v[8:11]
	v_mfma_f32_16x16x32_bf16 v[4:7], v[172:175], v[216:219], v[4:7]
	v_mfma_f32_16x16x32_bf16 v[0:3], v[184:187], v[216:219], v[0:3]
	v_mfma_f32_16x16x32_bf16 v[44:47], v[180:183], v[196:199], v[44:47]
	v_mfma_f32_16x16x32_bf16 v[40:43], v[188:191], v[196:199], v[40:43]
	v_mfma_f32_16x16x32_bf16 v[28:31], v[180:183], v[204:207], v[28:31]
	v_mfma_f32_16x16x32_bf16 v[24:27], v[188:191], v[204:207], v[24:27]
	v_mfma_f32_16x16x32_bf16 v[12:15], v[180:183], v[212:215], v[12:15]
	v_mfma_f32_16x16x32_bf16 v[8:11], v[188:191], v[212:215], v[8:11]
	v_mfma_f32_16x16x32_bf16 v[4:7], v[180:183], v[220:223], v[4:7]
	v_mfma_f32_16x16x32_bf16 v[0:3], v[188:191], v[220:223], v[0:3]
	s_setprio 0
	s_barrier
	s_add_u32 s94, s94, 0x100
	s_addc_u32 s95, s95, 0
	s_add_u32 s49, s49, 0x100
	s_addc_u32 s76, s76, 0
	s_cmp_ge_u32 s78, s45
	s_mov_b32 s77, s78
	s_cbranch_scc0 .LBB0_962
	s_setprio 2
	s_mov_b64 s[94:95], -1
	s_and_b64 vcc, exec, s[50:51]
	s_cbranch_vccz .LBB0_965
	s_mov_b32 s49, s92
	s_ashr_i32 s47, s46, 31
	s_ashr_i32 s45, s44, 31
	s_lshl_b64 s[4:5], s[46:47], 20
	s_lshl_b64 s[42:43], s[44:45], 9
	s_lshl_b64 s[48:49], s[48:49], 23
	v_readlane_b32 s50, v251, 28
	v_readlane_b32 s51, v251, 29
	s_add_u32 s17, s50, s42
	s_addc_u32 s27, s51, s43
	s_add_u32 s17, s17, s48
	s_addc_u32 s27, s27, s49
	s_add_u32 s4, s17, s4
	s_addc_u32 s5, s27, s5
	s_add_u32 s4, s4, 0xfc000000
	s_addc_u32 s5, s5, -1
	s_mov_b64 s[94:95], 0

; #define PG8_STAGE(bufoff, gbase, voff) do { _Pragma("unroll") for (int _i = 0; _i < 2; ++_i) \
;         __builtin_amdgcn_global_load_lds((const unsigned*)((const char*)(gbase) + (voff)[_i]), (LAS unsigned*)(lds + (bufoff) + ldsw + _i * 8192), 16, 0, 0); } while (0)
; #define PG8_LDA(dst, b, h) do { _Pragma("unroll") for (int m = 0; m < 4; ++m) _Pragma("unroll") for (int k = 0; k < 2; ++k) dst[m][k] = *(const LAS bf16x8*)(lds + PG8_SA(b, h) + aoff + m * 2048 + k * 1024); } while (0)
; #define PG8_LDB(dst, b, h) do { _Pragma("unroll") for (int n = 0; n < 2; ++n) _Pragma("unroll") for (int k = 0; k < 2; ++k) dst[n][k] = *(const LAS bf16x8*)(lds + PG8_SB(b, h) + boff + n * 2048 + k * 1024); } while (0)
; #define PG8_MMA(ai, bj, At, Bt) do { __builtin_amdgcn_s_setprio(1); _Pragma("unroll") for (int m = 0; m < 4; ++m) _Pragma("unroll") for (int n = 0; n < 2; ++n) _Pragma("unroll") for (int k = 0; k < 2; ++k) \
;         acc[ai][bj][m][n] = __builtin_amdgcn_mfma_f32_16x16x32_bf16(Bt[n][k], At[m][k], acc[ai][bj][m][n], 0, 0, 0); __builtin_amdgcn_s_setprio(0); } while (0)
; #define PG8_WAIT_V(n) asm volatile("s_waitcnt vmcnt(" #n ")" ::: "memory")
; #define PG8_WAIT_L(n) asm volatile("s_waitcnt lgkmcnt(" #n ")" ::: "memory")
; #define PG8_BAR __builtin_amdgcn_s_barrier()
; #define PG8_SCHED __builtin_amdgcn_sched_barrier(0)
; template <class Epi, class Sched, bool ALIGN_EPI>
; __device__ __forceinline__ void gemm_phase(LAS unsigned char* lds, const int wid, const int lda_, const int ldb_, const int K_, const Sched& S, const Epi& E) {
;     ...
;             PG8_LDB(B0, 1, 0); PG8_LDB(B1, 1, 1); PG8_SCHED; PG8_LDA(At, 1, 0); PG8_STAGE(PG8_SA(0, 1), a2 + hstepA, voffA);
;             PG8_WAIT_V(8); PG8_WAIT_L(0); PG8_BAR; PG8_MMA(0, 0, At, B0); PG8_MMA(0, 1, At, B1); PG8_BAR; PG8_SCHED;
;             PG8_LDA(At, 1, 1); PG8_STAGE(PG8_SB(1, 0), b3, voffB); PG8_STAGE(PG8_SB(1, 1), b3 + hstepB, voffB); PG8_STAGE(PG8_SA(1, 0), a3, voffA);
;             PG8_WAIT_V(8); PG8_WAIT_L(0); PG8_BAR; PG8_MMA(1, 0, At, B0); PG8_MMA(1, 1, At, B1); PG8_BAR; PG8_SCHED;
.Lgemm_join_1120:
	s_add_i32 s17, 0, 0x18000
	v_add_u32_e32 v141, s17, v135
	s_add_i32 s27, 0, 0x1c000
	ds_read_b128 v[160:163], v141
	ds_read_b128 v[164:167], v141 offset:1024
	ds_read_b128 v[168:171], v141 offset:2048
	ds_read_b128 v[172:175], v141 offset:3072
	v_add_u32_e32 v141, s27, v135
	ds_read_b128 v[180:183], v141
	ds_read_b128 v[184:187], v141 offset:1024
	ds_read_b128 v[188:191], v141 offset:2048
	ds_read_b128 v[192:195], v141 offset:3072
	s_add_u32 s80, s94, s10
	s_addc_u32 s81, s95, s11
	s_mov_b32 m0, s39
	v_lshl_add_u64 v[248:249], s[80:81], 0, v[132:133]
	ds_read_b128 v[196:199], v139 offset:32768
	ds_read_b128 v[200:203], v139 offset:33792
	ds_read_b128 v[204:207], v139 offset:34816
	ds_read_b128 v[208:211], v139 offset:35840
	ds_read_b128 v[212:215], v139 offset:36864
	ds_read_b128 v[216:219], v139 offset:37888
	ds_read_b128 v[220:223], v139 offset:38912
	ds_read_b128 v[224:227], v139 offset:39936
	global_load_lds_dwordx4 v[248:249], off
	v_lshl_add_u64 v[248:249], s[80:81], 0, v[130:131]
	s_mov_b32 m0, s72
	s_nop 0
	global_load_lds_dwordx4 v[248:249], off
	s_waitcnt vmcnt(8)
	s_waitcnt lgkmcnt(0)
	s_barrier
	s_setprio 1
	s_waitcnt lgkmcnt(0)
	v_mfma_f32_16x16x32_bf16 v[124:127], v[160:163], v[196:199], v[124:127]
	v_mfma_f32_16x16x32_bf16 v[120:123], v[168:171], v[196:199], v[120:123]
	v_mfma_f32_16x16x32_bf16 v[116:119], v[160:163], v[204:207], v[116:119]
	v_mfma_f32_16x16x32_bf16 v[112:115], v[168:171], v[204:207], v[112:115]
	v_mfma_f32_16x16x32_bf16 v[100:103], v[160:163], v[212:215], v[100:103]
	v_mfma_f32_16x16x32_bf16 v[96:99], v[168:171], v[212:215], v[96:99]
	v_mfma_f32_16x16x32_bf16 v[84:87], v[160:163], v[220:223], v[84:87]
	v_mfma_f32_16x16x32_bf16 v[80:83], v[168:171], v[220:223], v[80:83]
	v_mfma_f32_16x16x32_bf16 v[124:127], v[164:167], v[200:203], v[124:127]
	v_mfma_f32_16x16x32_bf16 v[120:123], v[172:175], v[200:203], v[120:123]
	v_mfma_f32_16x16x32_bf16 v[116:119], v[164:167], v[208:211], v[116:119]
	v_mfma_f32_16x16x32_bf16 v[112:115], v[172:175], v[208:211], v[112:115]
	v_mfma_f32_16x16x32_bf16 v[100:103], v[164:167], v[216:219], v[100:103]
	v_mfma_f32_16x16x32_bf16 v[96:99], v[172:175], v[216:219], v[96:99]
	v_mfma_f32_16x16x32_bf16 v[84:87], v[164:167], v[224:227], v[84:87]
	v_mfma_f32_16x16x32_bf16 v[80:83], v[172:175], v[224:227], v[80:83]
	s_setprio 0
	s_setprio 1
	v_mfma_f32_16x16x32_bf16 v[108:111], v[180:183], v[196:199], v[108:111]
	v_mfma_f32_16x16x32_bf16 v[104:107], v[188:191], v[196:199], v[104:107]
	v_mfma_f32_16x16x32_bf16 v[92:95], v[180:183], v[204:207], v[92:95]
	v_mfma_f32_16x16x32_bf16 v[88:91], v[188:191], v[204:207], v[88:91]
	v_mfma_f32_16x16x32_bf16 v[76:79], v[180:183], v[212:215], v[76:79]
	v_mfma_f32_16x16x32_bf16 v[72:75], v[188:191], v[212:215], v[72:75]
	v_mfma_f32_16x16x32_bf16 v[68:71], v[180:183], v[220:223], v[68:71]
	v_mfma_f32_16x16x32_bf16 v[64:67], v[188:191], v[220:223], v[64:67]
	v_mfma_f32_16x16x32_bf16 v[108:111], v[184:187], v[200:203], v[108:111]
	v_mfma_f32_16x16x32_bf16 v[104:107], v[192:195], v[200:203], v[104:107]
	v_mfma_f32_16x16x32_bf16 v[92:95], v[184:187], v[208:211], v[92:95]
	v_mfma_f32_16x16x32_bf16 v[88:91], v[192:195], v[208:211], v[88:91]
	v_mfma_f32_16x16x32_bf16 v[76:79], v[184:187], v[216:219], v[76:79]
	v_mfma_f32_16x16x32_bf16 v[72:75], v[192:195], v[216:219], v[72:75]
	v_mfma_f32_16x16x32_bf16 v[68:71], v[184:187], v[224:227], v[68:71]
	v_mfma_f32_16x16x32_bf16 v[64:67], v[192:195], v[224:227], v[64:67]
	s_setprio 0
	s_barrier
	s_add_i32 s17, s17, s3
	v_lshl_add_u64 v[228:229], v[228:229], 0, s[24:25]
	s_mov_b32 m0, s17
	ds_read_b128 v[196:199], v139 offset:49152
	ds_read_b128 v[200:203], v139 offset:50176
	ds_read_b128 v[204:207], v139 offset:51200
	ds_read_b128 v[208:211], v139 offset:52224
	ds_read_b128 v[212:215], v139 offset:53248
	ds_read_b128 v[216:219], v139 offset:54272
	ds_read_b128 v[220:223], v139 offset:55296
	ds_read_b128 v[224:227], v139 offset:56320
	global_load_lds_dwordx4 v[228:229], off
	v_lshl_add_u64 v[228:229], v[230:231], 0, s[24:25]
	s_add_i32 m0, s17, 0x2000
	s_add_i32 s17, s27, s3
	global_load_lds_dwordx4 v[228:229], off
	v_lshl_add_u64 v[228:229], v[232:233], 0, s[24:25]
	s_mov_b32 m0, s17
	s_nop 0
	global_load_lds_dwordx4 v[228:229], off
	v_lshl_add_u64 v[228:229], v[234:235], 0, s[24:25]
	s_add_i32 m0, s17, 0x2000
	s_nop 0
	global_load_lds_dwordx4 v[228:229], off
	v_lshl_add_u64 v[228:229], v[236:237], 0, s[24:25]
	s_mov_b32 m0, s73
	s_nop 0
	global_load_lds_dwordx4 v[228:229], off
	v_lshl_add_u64 v[228:229], v[246:247], 0, s[24:25]
	s_mov_b32 m0, s74
	s_nop 0
	global_load_lds_dwordx4 v[228:229], off
	s_waitcnt vmcnt(8)
	s_waitcnt lgkmcnt(0)
	s_barrier
; __device__ __forceinline__ unsigned cvt_pk_bf16(float lo, float hi) { const f32x2 v = {lo, hi}; return __builtin_bit_cast(unsigned, __builtin_convertvector(v, bf16x2_t)); }
;     template <class Sched> __device__ __forceinline__ void operator()(const f32x4 (&acc)[2][2][4][2], const Unit& u, const Sched& S, int wr, int wc, int fr, int fq) const {
;         const int rl0 = wr * 64 + fr, cl0 = wc * 32 + 8 * fq;
;         char* uo; int ldo, kind; S.out(u, uo, ldo, kind);
;         asm volatile("" : "+s"(ldo));
;         if (kind == 0) {
;             bf16_t* base = (bf16_t*)uo;
; #pragma unroll
;             for (int ai = 0; ai < 2; ++ai)
; #pragma unroll
;                 for (int m = 0; m < 4; ++m) { bf16_t* rowp = base + (size_t)(rl0 + ai * HALF + m * 16) * ldo + cl0;
; #pragma unroll
;                     for (int bj = 0; bj < 2; ++bj) { const f32x4 v0 = acc[ai][bj][m][0], v1 = acc[ai][bj][m][1];
;                         u32x4 w; w.x = cvt_pk_bf16(v0[0], v0[1]); w.y = cvt_pk_bf16(v0[2], v0[3]); w.z = cvt_pk_bf16(v1[0], v1[1]); w.w = cvt_pk_bf16(v1[2], v1[3]);
;                         *(u32x4*)(rowp + bj * HALF) = w; } }
	s_setprio 1
	s_waitcnt lgkmcnt(0)
	v_mfma_f32_16x16x32_bf16 v[60:63], v[160:163], v[196:199], v[60:63]
	v_mfma_f32_16x16x32_bf16 v[56:59], v[168:171], v[196:199], v[56:59]
	v_mfma_f32_16x16x32_bf16 v[52:55], v[160:163], v[204:207], v[52:55]
	v_mfma_f32_16x16x32_bf16 v[48:51], v[168:171], v[204:207], v[48:51]
	v_mfma_f32_16x16x32_bf16 v[36:39], v[160:163], v[212:215], v[36:39]
	v_mfma_f32_16x16x32_bf16 v[32:35], v[168:171], v[212:215], v[32:35]
	v_mfma_f32_16x16x32_bf16 v[20:23], v[160:163], v[220:223], v[20:23]
	v_mfma_f32_16x16x32_bf16 v[16:19], v[168:171], v[220:223], v[16:19]
	v_mfma_f32_16x16x32_bf16 v[60:63], v[164:167], v[200:203], v[60:63]
	v_mfma_f32_16x16x32_bf16 v[56:59], v[172:175], v[200:203], v[56:59]
	v_mfma_f32_16x16x32_bf16 v[52:55], v[164:167], v[208:211], v[52:55]
	v_mfma_f32_16x16x32_bf16 v[48:51], v[172:175], v[208:211], v[48:51]
	v_mfma_f32_16x16x32_bf16 v[36:39], v[164:167], v[216:219], v[36:39]
	v_mfma_f32_16x16x32_bf16 v[32:35], v[172:175], v[216:219], v[32:35]
	v_mfma_f32_16x16x32_bf16 v[20:23], v[164:167], v[224:227], v[20:23]
	v_mfma_f32_16x16x32_bf16 v[16:19], v[172:175], v[224:227], v[16:19]
	s_setprio 0
	s_setprio 1
	v_mfma_f32_16x16x32_bf16 v[44:47], v[180:183], v[196:199], v[44:47]
	v_mfma_f32_16x16x32_bf16 v[40:43], v[188:191], v[196:199], v[40:43]
	v_mfma_f32_16x16x32_bf16 v[28:31], v[180:183], v[204:207], v[28:31]
	v_mfma_f32_16x16x32_bf16 v[24:27], v[188:191], v[204:207], v[24:27]
	v_mfma_f32_16x16x32_bf16 v[12:15], v[180:183], v[212:215], v[12:15]
	v_mfma_f32_16x16x32_bf16 v[8:11], v[188:191], v[212:215], v[8:11]
	v_mfma_f32_16x16x32_bf16 v[4:7], v[180:183], v[220:223], v[4:7]
	v_mfma_f32_16x16x32_bf16 v[0:3], v[188:191], v[220:223], v[0:3]
	v_mfma_f32_16x16x32_bf16 v[44:47], v[184:187], v[200:203], v[44:47]
	v_mfma_f32_16x16x32_bf16 v[40:43], v[192:195], v[200:203], v[40:43]
	v_mfma_f32_16x16x32_bf16 v[28:31], v[184:187], v[208:211], v[28:31]
	v_mfma_f32_16x16x32_bf16 v[24:27], v[192:195], v[208:211], v[24:27]
	v_mfma_f32_16x16x32_bf16 v[12:15], v[184:187], v[216:219], v[12:15]
	v_mfma_f32_16x16x32_bf16 v[8:11], v[192:195], v[216:219], v[8:11]
	v_mfma_f32_16x16x32_bf16 v[4:7], v[184:187], v[224:227], v[4:7]
	v_mfma_f32_16x16x32_bf16 v[0:3], v[192:195], v[224:227], v[0:3]
	s_setprio 0
	s_barrier
	s_add_i32 s78, s78, 2
	s_add_u32 s50, s50, 0x100
	s_addc_u32 s51, s51, 0
	s_cmp_gt_u32 s78, 29
	s_cbranch_scc0 .LBB0_1120
	s_setprio 2
	s_sub_i32 s4, s38, 22
	s_ashr_i32 s5, s38, 31
	s_cmp_lt_i32 s38, 22
	s_cselect_b32 s5, s5, 0
	s_cselect_b32 s4, s38, s4
	s_mov_b32 s17, 0x2bc00000
	s_cselect_b32 s17, 0x1f600000, s17
	s_lshl_b64 s[4:5], s[4:5], 9
	s_add_u32 s4, s66, s4
	s_addc_u32 s5, s67, s5
	s_add_u32 s4, s4, s17
	s_addc_u32 s5, s5, 0
	s_mul_i32 s27, s34, 0x2c0000
	s_mul_hi_i32 s17, s34, 0x2c0000
	s_add_u32 s4, s4, s27
	s_addc_u32 s5, s5, s17
	s_movk_i32 s17, 0x1600
	v_lshl_add_u64 v[156:157], v[136:137], 1, s[4:5]
	v_mad_i64_i32 v[158:159], s[4:5], s17, v134, 0
	v_lshl_add_u64 v[158:159], v[158:159], 1, v[156:157]
	v_cvt_pk_bf16_f32 v108, v108, v109
	v_cvt_pk_bf16_f32 v109, v110, v111
	v_cvt_pk_bf16_f32 v110, v104, v105
	v_cvt_pk_bf16_f32 v111, v106, v107
	v_mad_i64_i32 v[104:105], s[4:5], s17, v138, 0
	v_cvt_pk_bf16_f32 v124, v124, v125
	v_cvt_pk_bf16_f32 v125, v126, v127
	v_cvt_pk_bf16_f32 v126, v120, v121
	v_cvt_pk_bf16_f32 v127, v122, v123
	global_store_dwordx4 v[158:159], v[108:111], off offset:256
	v_cvt_pk_bf16_f32 v92, v92, v93
	v_cvt_pk_bf16_f32 v93, v94, v95
	v_lshl_add_u64 v[108:109], v[104:105], 1, v[156:157]
	v_cvt_pk_bf16_f32 v94, v88, v89
	v_cvt_pk_bf16_f32 v95, v90, v91
	v_mad_i64_i32 v[88:89], s[4:5], s17, v140, 0
	global_store_dwordx4 v[158:159], v[124:127], off
	v_cvt_pk_bf16_f32 v104, v116, v117
	v_cvt_pk_bf16_f32 v105, v118, v119
	v_cvt_pk_bf16_f32 v106, v112, v113
	v_cvt_pk_bf16_f32 v107, v114, v115
	global_store_dwordx4 v[108:109], v[92:95], off offset:256
	v_cvt_pk_bf16_f32 v76, v76, v77
	v_cvt_pk_bf16_f32 v77, v78, v79
	v_lshl_add_u64 v[92:93], v[88:89], 1, v[156:157]
	v_cvt_pk_bf16_f32 v78, v72, v73
	v_cvt_pk_bf16_f32 v79, v74, v75
	v_mad_i64_i32 v[72:73], s[4:5], s17, v142, 0
	v_cvt_pk_bf16_f32 v68, v68, v69
	v_cvt_pk_bf16_f32 v69, v70, v71
	v_cvt_pk_bf16_f32 v70, v64, v65
	v_mad_i64_i32 v[64:65], s[4:5], s17, v144, 0
	global_store_dwordx4 v[108:109], v[104:107], off
	v_cvt_pk_bf16_f32 v88, v100, v101
	v_cvt_pk_bf16_f32 v89, v102, v103
	v_cvt_pk_bf16_f32 v90, v96, v97
	v_cvt_pk_bf16_f32 v91, v98, v99
	global_store_dwordx4 v[92:93], v[76:79], off offset:256
	v_cvt_pk_bf16_f32 v74, v80, v81
	v_cvt_pk_bf16_f32 v75, v82, v83
	v_lshl_add_u64 v[76:77], v[72:73], 1, v[156:157]
	v_cvt_pk_bf16_f32 v72, v84, v85
	v_cvt_pk_bf16_f32 v73, v86, v87
	v_cvt_pk_bf16_f32 v71, v66, v67
	v_lshl_add_u64 v[64:65], v[64:65], 1, v[156:157]
	v_cvt_pk_bf16_f32 v44, v44, v45
	v_cvt_pk_bf16_f32 v45, v46, v47
	v_cvt_pk_bf16_f32 v46, v40, v41
	v_cvt_pk_bf16_f32 v47, v42, v43
	v_mad_i64_i32 v[40:41], s[4:5], s17, v146, 0
	global_store_dwordx4 v[92:93], v[88:91], off
	global_store_dwordx4 v[76:77], v[72:75], off
	global_store_dwordx4 v[76:77], v[68:71], off offset:256
	v_cvt_pk_bf16_f32 v60, v60, v61
	v_cvt_pk_bf16_f32 v61, v62, v63
	v_cvt_pk_bf16_f32 v62, v56, v57
	v_cvt_pk_bf16_f32 v63, v58, v59
	global_store_dwordx4 v[64:65], v[44:47], off offset:256
	v_cvt_pk_bf16_f32 v28, v28, v29
	v_cvt_pk_bf16_f32 v29, v30, v31
	v_lshl_add_u64 v[44:45], v[40:41], 1, v[156:157]
	v_cvt_pk_bf16_f32 v30, v24, v25
	v_cvt_pk_bf16_f32 v31, v26, v27
	v_mad_i64_i32 v[24:25], s[4:5], s17, v148, 0
	global_store_dwordx4 v[64:65], v[60:63], off
	v_cvt_pk_bf16_f32 v40, v52, v53
	v_cvt_pk_bf16_f32 v41, v54, v55
	v_cvt_pk_bf16_f32 v42, v48, v49
	v_cvt_pk_bf16_f32 v43, v50, v51
	global_store_dwordx4 v[44:45], v[28:31], off offset:256
	v_cvt_pk_bf16_f32 v12, v12, v13
	v_cvt_pk_bf16_f32 v13, v14, v15
	v_lshl_add_u64 v[28:29], v[24:25], 1, v[156:157]
	v_cvt_pk_bf16_f32 v14, v8, v9
	v_cvt_pk_bf16_f32 v15, v10, v11
	v_mad_i64_i32 v[8:9], s[4:5], s17, v150, 0
	global_store_dwordx4 v[44:45], v[40:43], off
	v_cvt_pk_bf16_f32 v24, v36, v37
	v_cvt_pk_bf16_f32 v25, v38, v39
	v_cvt_pk_bf16_f32 v26, v32, v33
	v_cvt_pk_bf16_f32 v27, v34, v35
	global_store_dwordx4 v[28:29], v[12:15], off offset:256
	v_cvt_pk_bf16_f32 v10, v16, v17
	v_cvt_pk_bf16_f32 v11, v18, v19
	v_lshl_add_u64 v[12:13], v[8:9], 1, v[156:157]
	v_cvt_pk_bf16_f32 v8, v20, v21
	v_cvt_pk_bf16_f32 v9, v22, v23
	v_cvt_pk_bf16_f32 v4, v4, v5
	v_cvt_pk_bf16_f32 v5, v6, v7
	v_cvt_pk_bf16_f32 v6, v0, v1
	v_cvt_pk_bf16_f32 v7, v2, v3
	s_and_b64 vcc, exec, s[36:37]
	s_mov_b32 s38, s42
	s_mov_b32 s34, s44
	s_mov_b64 s[50:51], s[48:49]
	s_mov_b64 s[40:41], s[46:47]
	global_store_dwordx4 v[28:29], v[24:27], off
	global_store_dwordx4 v[12:13], v[8:11], off
	global_store_dwordx4 v[12:13], v[4:7], off offset:256
	s_cbranch_vccz .LBB0_1117
	v_readlane_b32 s4, v253, 1
	s_waitcnt vmcnt(0)
	v_readlane_b32 s5, v253, 2
	s_andn2_b64 vcc, exec, s[4:5]
	s_cbranch_vccnz .LBB0_1124
	s_barrier

; #define PG8_STAGE(bufoff, gbase, voff) do { _Pragma("unroll") for (int _i = 0; _i < 2; ++_i) \
;         __builtin_amdgcn_global_load_lds((const unsigned*)((const char*)(gbase) + (voff)[_i]), (LAS unsigned*)(lds + (bufoff) + ldsw + _i * 8192), 16, 0, 0); } while (0)
; #define PG8_LDA(dst, b, h) do { _Pragma("unroll") for (int m = 0; m < 4; ++m) _Pragma("unroll") for (int k = 0; k < 2; ++k) dst[m][k] = *(const LAS bf16x8*)(lds + PG8_SA(b, h) + aoff + m * 2048 + k * 1024); } while (0)
; #define PG8_LDB(dst, b, h) do { _Pragma("unroll") for (int n = 0; n < 2; ++n) _Pragma("unroll") for (int k = 0; k < 2; ++k) dst[n][k] = *(const LAS bf16x8*)(lds + PG8_SB(b, h) + boff + n * 2048 + k * 1024); } while (0)
; #define PG8_MMA(ai, bj, At, Bt) do { __builtin_amdgcn_s_setprio(1); _Pragma("unroll") for (int m = 0; m < 4; ++m) _Pragma("unroll") for (int n = 0; n < 2; ++n) _Pragma("unroll") for (int k = 0; k < 2; ++k) \
;         acc[ai][bj][m][n] = __builtin_amdgcn_mfma_f32_16x16x32_bf16(Bt[n][k], At[m][k], acc[ai][bj][m][n], 0, 0, 0); __builtin_amdgcn_s_setprio(0); } while (0)
; #define PG8_WAIT_V(n) asm volatile("s_waitcnt vmcnt(" #n ")" ::: "memory")
; #define PG8_WAIT_L(n) asm volatile("s_waitcnt lgkmcnt(" #n ")" ::: "memory")
; #define PG8_BAR __builtin_amdgcn_s_barrier()
; #define PG8_SCHED __builtin_amdgcn_sched_barrier(0)
; template <class Epi, class Sched, bool ALIGN_EPI>
; __device__ __forceinline__ void gemm_phase(LAS unsigned char* lds, const int wid, const int lda_, const int ldb_, const int K_, const Sched& S, const Epi& E) {
;     ...
;             PG8_LDB(B0, 1, 0); PG8_LDB(B1, 1, 1); PG8_SCHED; PG8_LDA(At, 1, 0); PG8_STAGE(PG8_SA(0, 1), a2 + hstepA, voffA);
;             PG8_WAIT_V(8); PG8_WAIT_L(0); PG8_BAR; PG8_MMA(0, 0, At, B0); PG8_MMA(0, 1, At, B1); PG8_BAR; PG8_SCHED;
.Lgemm_join_1341:
	s_add_i32 s17, 0, 0x18000
	v_add_u32_e32 v141, s17, v135
	s_add_i32 s27, 0, 0x1c000
	ds_read_b128 v[156:159], v141
	ds_read_b128 v[160:163], v141 offset:1024
	ds_read_b128 v[164:167], v141 offset:2048
	ds_read_b128 v[168:171], v141 offset:3072
	v_add_u32_e32 v141, s27, v135
	ds_read_b128 v[172:175], v141
	ds_read_b128 v[180:183], v141 offset:1024
	ds_read_b128 v[184:187], v141 offset:2048
	ds_read_b128 v[188:191], v141 offset:3072
	s_add_u32 s48, s48, s0
	s_addc_u32 s49, s49, s1
	s_mov_b32 m0, s15
	v_lshl_add_u64 v[236:237], s[48:49], 0, v[128:129]
	ds_read_b128 v[192:195], v139 offset:32768
	ds_read_b128 v[196:199], v139 offset:33792
	ds_read_b128 v[200:203], v139 offset:34816
	ds_read_b128 v[204:207], v139 offset:35840
	ds_read_b128 v[208:211], v139 offset:36864
	ds_read_b128 v[212:215], v139 offset:37888
	ds_read_b128 v[216:219], v139 offset:38912
	ds_read_b128 v[220:223], v139 offset:39936
	global_load_lds_dwordx4 v[236:237], off
	v_lshl_add_u64 v[236:237], s[48:49], 0, v[130:131]
	s_mov_b32 m0, s26
	s_nop 0
	global_load_lds_dwordx4 v[236:237], off
	s_waitcnt vmcnt(8)
	s_waitcnt lgkmcnt(0)
	s_barrier
	s_setprio 1
	s_waitcnt lgkmcnt(0)
	v_mfma_f32_16x16x32_bf16 v[124:127], v[156:159], v[192:195], v[124:127]
	v_mfma_f32_16x16x32_bf16 v[120:123], v[164:167], v[192:195], v[120:123]
	v_mfma_f32_16x16x32_bf16 v[116:119], v[156:159], v[200:203], v[116:119]
	v_mfma_f32_16x16x32_bf16 v[112:115], v[164:167], v[200:203], v[112:115]
	v_mfma_f32_16x16x32_bf16 v[100:103], v[156:159], v[208:211], v[100:103]
	v_mfma_f32_16x16x32_bf16 v[96:99], v[164:167], v[208:211], v[96:99]
	v_mfma_f32_16x16x32_bf16 v[84:87], v[156:159], v[216:219], v[84:87]
	v_mfma_f32_16x16x32_bf16 v[80:83], v[164:167], v[216:219], v[80:83]
	v_mfma_f32_16x16x32_bf16 v[124:127], v[160:163], v[196:199], v[124:127]
	v_mfma_f32_16x16x32_bf16 v[120:123], v[168:171], v[196:199], v[120:123]
	v_mfma_f32_16x16x32_bf16 v[116:119], v[160:163], v[204:207], v[116:119]
	v_mfma_f32_16x16x32_bf16 v[112:115], v[168:171], v[204:207], v[112:115]
	v_mfma_f32_16x16x32_bf16 v[100:103], v[160:163], v[212:215], v[100:103]
	v_mfma_f32_16x16x32_bf16 v[96:99], v[168:171], v[212:215], v[96:99]
	v_mfma_f32_16x16x32_bf16 v[84:87], v[160:163], v[220:223], v[84:87]
	v_mfma_f32_16x16x32_bf16 v[80:83], v[168:171], v[220:223], v[80:83]
	s_setprio 0
	s_setprio 1
	v_mfma_f32_16x16x32_bf16 v[108:111], v[172:175], v[192:195], v[108:111]
	v_mfma_f32_16x16x32_bf16 v[104:107], v[184:187], v[192:195], v[104:107]
	v_mfma_f32_16x16x32_bf16 v[92:95], v[172:175], v[200:203], v[92:95]
	v_mfma_f32_16x16x32_bf16 v[88:91], v[184:187], v[200:203], v[88:91]
	v_mfma_f32_16x16x32_bf16 v[76:79], v[172:175], v[208:211], v[76:79]
	v_mfma_f32_16x16x32_bf16 v[72:75], v[184:187], v[208:211], v[72:75]
	v_mfma_f32_16x16x32_bf16 v[68:71], v[172:175], v[216:219], v[68:71]
	v_mfma_f32_16x16x32_bf16 v[64:67], v[184:187], v[216:219], v[64:67]
	v_mfma_f32_16x16x32_bf16 v[108:111], v[180:183], v[196:199], v[108:111]
	v_mfma_f32_16x16x32_bf16 v[104:107], v[188:191], v[196:199], v[104:107]
	v_mfma_f32_16x16x32_bf16 v[92:95], v[180:183], v[204:207], v[92:95]
	v_mfma_f32_16x16x32_bf16 v[88:91], v[188:191], v[204:207], v[88:91]
	v_mfma_f32_16x16x32_bf16 v[76:79], v[180:183], v[212:215], v[76:79]
	v_mfma_f32_16x16x32_bf16 v[72:75], v[188:191], v[212:215], v[72:75]
	v_mfma_f32_16x16x32_bf16 v[68:71], v[180:183], v[220:223], v[68:71]
	v_mfma_f32_16x16x32_bf16 v[64:67], v[188:191], v[220:223], v[64:67]
	s_setprio 0
	s_barrier
; #define PG8_STAGE(bufoff, gbase, voff) do { _Pragma("unroll") for (int _i = 0; _i < 2; ++_i) \
;         __builtin_amdgcn_global_load_lds((const unsigned*)((const char*)(gbase) + (voff)[_i]), (LAS unsigned*)(lds + (bufoff) + ldsw + _i * 8192), 16, 0, 0); } while (0)
; #define PG8_LDA(dst, b, h) do { _Pragma("unroll") for (int m = 0; m < 4; ++m) _Pragma("unroll") for (int k = 0; k < 2; ++k) dst[m][k] = *(const LAS bf16x8*)(lds + PG8_SA(b, h) + aoff + m * 2048 + k * 1024); } while (0)
; #define PG8_MMA(ai, bj, At, Bt) do { __builtin_amdgcn_s_setprio(1); _Pragma("unroll") for (int m = 0; m < 4; ++m) _Pragma("unroll") for (int n = 0; n < 2; ++n) _Pragma("unroll") for (int k = 0; k < 2; ++k) \
;         acc[ai][bj][m][n] = __builtin_amdgcn_mfma_f32_16x16x32_bf16(Bt[n][k], At[m][k], acc[ai][bj][m][n], 0, 0, 0); __builtin_amdgcn_s_setprio(0); } while (0)
; #define PG8_WAIT_V(n) asm volatile("s_waitcnt vmcnt(" #n ")" ::: "memory")
; #define PG8_WAIT_L(n) asm volatile("s_waitcnt lgkmcnt(" #n ")" ::: "memory")
; #define PG8_BAR __builtin_amdgcn_s_barrier()
; #define PG8_SCHED __builtin_amdgcn_sched_barrier(0)
; template <class Epi, class Sched, bool ALIGN_EPI>
; __device__ __forceinline__ void gemm_phase(LAS unsigned char* lds, const int wid, const int lda_, const int ldb_, const int K_, const Sched& S, const Epi& E) {
;     ...
;             PG8_LDA(At, 1, 1); PG8_STAGE(PG8_SB(1, 0), b3, voffB); PG8_STAGE(PG8_SB(1, 1), b3 + hstepB, voffB); PG8_STAGE(PG8_SA(1, 0), a3, voffA);
;             PG8_WAIT_V(8); PG8_WAIT_L(0); PG8_BAR; PG8_MMA(1, 0, At, B0); PG8_MMA(1, 1, At, B1); PG8_BAR; PG8_SCHED;
;         }
;         if constexpr (ALIGN_EPI) { if (wr == 0) PG8_BAR; }
;         E(acc, cur, S, wr, wc, fr, fq);
;         if (!has_next) break;
;     __device__ __forceinline__ void out(const pg8::Unit& u, char*& o, int& ldo, int& kind) const { ldo = D;
;         if (u.kq < 0) { o = (char*)ws + YOFF + ((size_t)u.pm * 256 * D + (size_t)u.pn * 256) * 2; kind = 0; }
;         else { o = (char*)ws + WS_PART + (((size_t)u.kq * MCTX + (size_t)(u.pm - 64) * 256) * D + (size_t)u.pn * 256) * 2; kind = 0; } }
	s_add_i32 s17, s17, s3
	v_lshl_add_u64 v[224:225], v[224:225], 0, s[24:25]
	s_mov_b32 m0, s17
	ds_read_b128 v[192:195], v139 offset:49152
	ds_read_b128 v[196:199], v139 offset:50176
	ds_read_b128 v[200:203], v139 offset:51200
	ds_read_b128 v[204:207], v139 offset:52224
	ds_read_b128 v[208:211], v139 offset:53248
	ds_read_b128 v[212:215], v139 offset:54272
	ds_read_b128 v[216:219], v139 offset:55296
	ds_read_b128 v[220:223], v139 offset:56320
	global_load_lds_dwordx4 v[224:225], off
	v_lshl_add_u64 v[224:225], v[226:227], 0, s[24:25]
	s_add_i32 m0, s17, 0x2000
	s_add_i32 s17, s27, s3
	global_load_lds_dwordx4 v[224:225], off
	v_lshl_add_u64 v[224:225], v[228:229], 0, s[24:25]
	s_mov_b32 m0, s17
	s_nop 0
	global_load_lds_dwordx4 v[224:225], off
	v_lshl_add_u64 v[224:225], v[230:231], 0, s[24:25]
	s_add_i32 m0, s17, 0x2000
	s_nop 0
	global_load_lds_dwordx4 v[224:225], off
	v_lshl_add_u64 v[224:225], v[232:233], 0, s[24:25]
	s_mov_b32 m0, s50
	s_nop 0
	global_load_lds_dwordx4 v[224:225], off
	v_lshl_add_u64 v[224:225], v[234:235], 0, s[24:25]
	s_mov_b32 m0, s51
	s_nop 0
	global_load_lds_dwordx4 v[224:225], off
	s_waitcnt vmcnt(8)
	s_waitcnt lgkmcnt(0)
	s_barrier
	s_setprio 1
	s_waitcnt lgkmcnt(0)
	v_mfma_f32_16x16x32_bf16 v[60:63], v[156:159], v[192:195], v[60:63]
	v_mfma_f32_16x16x32_bf16 v[56:59], v[164:167], v[192:195], v[56:59]
	v_mfma_f32_16x16x32_bf16 v[52:55], v[156:159], v[200:203], v[52:55]
	v_mfma_f32_16x16x32_bf16 v[48:51], v[164:167], v[200:203], v[48:51]
	v_mfma_f32_16x16x32_bf16 v[36:39], v[156:159], v[208:211], v[36:39]
	v_mfma_f32_16x16x32_bf16 v[32:35], v[164:167], v[208:211], v[32:35]
	v_mfma_f32_16x16x32_bf16 v[20:23], v[156:159], v[216:219], v[20:23]
	v_mfma_f32_16x16x32_bf16 v[16:19], v[164:167], v[216:219], v[16:19]
	v_mfma_f32_16x16x32_bf16 v[60:63], v[160:163], v[196:199], v[60:63]
	v_mfma_f32_16x16x32_bf16 v[56:59], v[168:171], v[196:199], v[56:59]
	v_mfma_f32_16x16x32_bf16 v[52:55], v[160:163], v[204:207], v[52:55]
	v_mfma_f32_16x16x32_bf16 v[48:51], v[168:171], v[204:207], v[48:51]
	v_mfma_f32_16x16x32_bf16 v[36:39], v[160:163], v[212:215], v[36:39]
	v_mfma_f32_16x16x32_bf16 v[32:35], v[168:171], v[212:215], v[32:35]
	v_mfma_f32_16x16x32_bf16 v[20:23], v[160:163], v[220:223], v[20:23]
	v_mfma_f32_16x16x32_bf16 v[16:19], v[168:171], v[220:223], v[16:19]
	s_setprio 0
	s_setprio 1
	v_mfma_f32_16x16x32_bf16 v[44:47], v[172:175], v[192:195], v[44:47]
	v_mfma_f32_16x16x32_bf16 v[40:43], v[184:187], v[192:195], v[40:43]
	v_mfma_f32_16x16x32_bf16 v[28:31], v[172:175], v[200:203], v[28:31]
	v_mfma_f32_16x16x32_bf16 v[24:27], v[184:187], v[200:203], v[24:27]
	v_mfma_f32_16x16x32_bf16 v[12:15], v[172:175], v[208:211], v[12:15]
	v_mfma_f32_16x16x32_bf16 v[8:11], v[184:187], v[208:211], v[8:11]
	v_mfma_f32_16x16x32_bf16 v[4:7], v[172:175], v[216:219], v[4:7]
	v_mfma_f32_16x16x32_bf16 v[0:3], v[184:187], v[216:219], v[0:3]
	v_mfma_f32_16x16x32_bf16 v[44:47], v[180:183], v[196:199], v[44:47]
	v_mfma_f32_16x16x32_bf16 v[40:43], v[188:191], v[196:199], v[40:43]
	v_mfma_f32_16x16x32_bf16 v[28:31], v[180:183], v[204:207], v[28:31]
	v_mfma_f32_16x16x32_bf16 v[24:27], v[188:191], v[204:207], v[24:27]
	v_mfma_f32_16x16x32_bf16 v[12:15], v[180:183], v[212:215], v[12:15]
	v_mfma_f32_16x16x32_bf16 v[8:11], v[188:191], v[212:215], v[8:11]
	v_mfma_f32_16x16x32_bf16 v[4:7], v[180:183], v[220:223], v[4:7]
	v_mfma_f32_16x16x32_bf16 v[0:3], v[188:191], v[220:223], v[0:3]
	s_setprio 0
	s_barrier
	s_add_u32 s46, s46, 0x100
	s_addc_u32 s47, s47, 0
	s_add_u32 s31, s31, 0x100
	s_addc_u32 s35, s35, 0
	s_cmp_ge_u32 s76, s4
	s_mov_b32 s39, s76
	s_cbranch_scc0 .LBB0_1341
	s_setprio 2
	s_mov_b64 s[46:47], -1
	s_and_b64 vcc, exec, s[44:45]
	s_cbranch_vccz .LBB0_1344
	s_mov_b32 s39, s92
	s_ashr_i32 s31, s30, 31
	s_ashr_i32 s35, s34, 31
	s_lshl_b64 s[4:5], s[30:31], 20
	s_lshl_b64 s[44:45], s[34:35], 9
	s_lshl_b64 s[38:39], s[38:39], 23
	v_readlane_b32 s46, v251, 28
	v_readlane_b32 s47, v251, 29
	s_add_u32 s17, s46, s44
	s_addc_u32 s27, s47, s45
	s_add_u32 s17, s17, s38
	s_addc_u32 s27, s27, s39
	s_add_u32 s4, s17, s4
	s_addc_u32 s5, s27, s5
	s_add_u32 s4, s4, 0xfc000000
	s_addc_u32 s5, s5, -1
	s_mov_b64 s[46:47], 0
